# rewritten residual/GLU epilogues: each group's store issued right after its cvt (counted vmcnt over mixed loads+stores) instead of all stores at the end
# speedup vs baseline: 1.0054x; 1.0038x over previous
; __device__ __forceinline__ unsigned cvt_pk_bf16(float lo, float hi) { unsigned r; asm("v_cvt_pk_bf16_f32 %0, %1, %2" : "=v"(r) : "v"(lo), "v"(hi)); return r; }
;     __device__ __forceinline__ void operator()(const Acc& acc, const Unit& u, int wr, int wc, int fr, int fq) const {
;         const bool isx = u.pm < 128; const int mb = isx ? (u.pm >> 4) : 8;
;         const size_t tile0 = (size_t)(isx ? u.pm : u.pm - 128) * 256 * D;
;         const float* sp32 = (const float*)(isx ? srcx : srcc) + tile0; const bf16_t* sp16 = (const bf16_t*)(isx ? srcx : srcc) + tile0;
;         float* dp32 = (float*)(isx ? dstx : dstc) + tile0; bf16_t* dp16 = (bf16_t*)(isx ? dstx : dstc) + tile0;
;         const int r0 = wr * 64 + fr, col0 = u.pn * 256 + wc * 32 + 8 * fq; const float* gp = gate + (size_t)mb * 9216 + col0;
;         f32x4 gv[2][2];
; #pragma unroll
;         for (int bj = 0; bj < 2; ++bj)
; #pragma unroll
;             for (int n = 0; n < 2; ++n) gv[bj][n] = *(const f32x4*)(gp + bj * 128 + n * 4) * f;
; #pragma unroll
;         for (int ai = 0; ai < 2; ++ai)
; #pragma unroll
;             for (int m = 0; m < 4; ++m) { const size_t off = (size_t)(r0 + ai * 128 + m * 16) * D + col0;
; #pragma unroll
;                 for (int bj = 0; bj < 2; ++bj) { const size_t o2 = off + bj * 128; f32x4 s0, s1;
;                     if (SRC32) { s0 = *(const f32x4*)(sp32 + o2); s1 = *(const f32x4*)(sp32 + o2 + 4); }
;                     else { const u32x4 q = *(const u32x4*)(sp16 + o2); s0 = (f32x4){bf2f(q.x & 0xffffu), bf2f(q.x >> 16), bf2f(q.y & 0xffffu), bf2f(q.y >> 16)}; s1 = (f32x4){bf2f(q.z & 0xffffu), bf2f(q.z >> 16), bf2f(q.w & 0xffffu), bf2f(q.w >> 16)}; }
;                     const f32x4 v0 = s0 + gv[bj][0] * acc[ai][bj][m][0], v1 = s1 + gv[bj][1] * acc[ai][bj][m][1];
;                     if (DST32) { *(f32x4*)(dp32 + o2) = v0; *(f32x4*)(dp32 + o2 + 4) = v1; }
;                     else { u32x4 w; w.x = cvt_pk_bf16(v0.x, v0.y); w.y = cvt_pk_bf16(v0.z, v0.w); w.z = cvt_pk_bf16(v1.x, v1.y); w.w = cvt_pk_bf16(v1.z, v1.w); *(u32x4*)(dp16 + o2) = w; } } }
.LBB0_357:
	s_ashr_i32 s0, s28, 4
	s_ashr_i32 s29, s28, 31
	s_mul_hi_i32 s33, s0, 0x9000
	s_mul_i32 s0, s0, 0x9000
	s_add_u32 s34, s52, s0
	s_addc_u32 s35, s53, s33
	v_lshl_or_b32 v204, s69, 8, v185
	v_lshlrev_b32_e32 v182, 2, v204
	global_load_dwordx4 v[174:177], v182, s[34:35]
	global_load_dwordx4 v[178:181], v182, s[34:35] offset:16
	global_load_dwordx4 v[188:191], v182, s[34:35] offset:512
	global_load_dwordx4 v[192:195], v182, s[34:35] offset:528
	s_lshl_b64 s[34:35], s[28:29], 20
	s_add_u32 s38, s36, s34
	s_addc_u32 s39, s37, s35
	s_lshl_b64 s[28:29], s[28:29], 19
	s_add_u32 s28, s86, s28
	s_addc_u32 s29, s87, s29
	v_add_lshl_u32 v183, v150, v204, 2
	global_load_dwordx4 v[196:199], v183, s[38:39]
	global_load_dwordx4 v[200:203], v183, s[38:39] offset:16
	v_add_lshl_u32 v182, v150, v204, 2
	global_load_dwordx4 v[208:211], v182, s[38:39] offset:512
	global_load_dwordx4 v[212:215], v182, s[38:39] offset:528
	v_add_lshl_u32 v183, v152, v204, 2
	global_load_dwordx4 v[216:219], v183, s[38:39]
	global_load_dwordx4 v[220:223], v183, s[38:39] offset:16
	v_add_lshl_u32 v182, v152, v204, 2
	global_load_dwordx4 v[224:227], v182, s[38:39] offset:512
	global_load_dwordx4 v[228:231], v182, s[38:39] offset:528
	v_add_lshl_u32 v183, v154, v204, 2
	global_load_dwordx4 v[232:235], v183, s[38:39]
	global_load_dwordx4 v[236:239], v183, s[38:39] offset:16
	v_add_lshl_u32 v182, v154, v204, 2
	global_load_dwordx4 v[240:243], v182, s[38:39] offset:512
	global_load_dwordx4 v[244:247], v182, s[38:39] offset:528
	s_waitcnt vmcnt(10)
	v_pk_mul_f32 v[174:175], v[174:175], 0.5 op_sel_hi:[1,0]
	v_pk_mul_f32 v[176:177], v[176:177], 0.5 op_sel_hi:[1,0]
	v_pk_mul_f32 v[178:179], v[178:179], 0.5 op_sel_hi:[1,0]
	v_pk_mul_f32 v[180:181], v[180:181], 0.5 op_sel_hi:[1,0]
	v_pk_mul_f32 v[188:189], v[188:189], 0.5 op_sel_hi:[1,0]
	v_pk_mul_f32 v[190:191], v[190:191], 0.5 op_sel_hi:[1,0]
	v_pk_mul_f32 v[192:193], v[192:193], 0.5 op_sel_hi:[1,0]
	v_pk_mul_f32 v[194:195], v[194:195], 0.5 op_sel_hi:[1,0]
	v_pk_fma_f32 v[124:125], v[124:125], v[174:175], v[196:197]
	v_pk_fma_f32 v[126:127], v[126:127], v[176:177], v[198:199]
	v_pk_fma_f32 v[120:121], v[120:121], v[178:179], v[200:201]
	v_pk_fma_f32 v[122:123], v[122:123], v[180:181], v[202:203]
	v_cvt_pk_bf16_f32 v124, v124, v125
	v_cvt_pk_bf16_f32 v125, v126, v127
	v_cvt_pk_bf16_f32 v126, v120, v121
	v_cvt_pk_bf16_f32 v127, v122, v123
	v_add_lshl_u32 v205, v150, v204, 1
	global_store_dwordx4 v205, v[124:127], s[28:29]
	v_add_lshl_u32 v183, v156, v204, 2
	global_load_dwordx4 v[196:199], v183, s[38:39]
	global_load_dwordx4 v[200:203], v183, s[38:39] offset:16
	s_waitcnt vmcnt(11)
	v_pk_fma_f32 v[116:117], v[116:117], v[188:189], v[208:209]
	v_pk_fma_f32 v[118:119], v[118:119], v[190:191], v[210:211]
	v_pk_fma_f32 v[112:113], v[112:113], v[192:193], v[212:213]
	v_pk_fma_f32 v[114:115], v[114:115], v[194:195], v[214:215]
	v_cvt_pk_bf16_f32 v116, v116, v117
	v_cvt_pk_bf16_f32 v117, v118, v119
	v_cvt_pk_bf16_f32 v118, v112, v113
	v_cvt_pk_bf16_f32 v119, v114, v115
	global_store_dwordx4 v205, v[116:119], s[28:29] offset:256
	v_add_lshl_u32 v182, v156, v204, 2
	global_load_dwordx4 v[208:211], v182, s[38:39] offset:512
	global_load_dwordx4 v[212:215], v182, s[38:39] offset:528
	s_waitcnt vmcnt(12)
	v_pk_fma_f32 v[108:109], v[108:109], v[174:175], v[216:217]
	v_pk_fma_f32 v[110:111], v[110:111], v[176:177], v[218:219]
	v_pk_fma_f32 v[104:105], v[104:105], v[178:179], v[220:221]
	v_pk_fma_f32 v[106:107], v[106:107], v[180:181], v[222:223]
	v_cvt_pk_bf16_f32 v108, v108, v109
	v_cvt_pk_bf16_f32 v109, v110, v111
	v_cvt_pk_bf16_f32 v110, v104, v105
	v_cvt_pk_bf16_f32 v111, v106, v107
	v_add_lshl_u32 v205, v152, v204, 1
	global_store_dwordx4 v205, v[108:111], s[28:29]
	v_add_lshl_u32 v183, v158, v204, 2
	global_load_dwordx4 v[216:219], v183, s[38:39]
	global_load_dwordx4 v[220:223], v183, s[38:39] offset:16
	s_waitcnt vmcnt(13)
	v_pk_fma_f32 v[100:101], v[100:101], v[188:189], v[224:225]
	v_pk_fma_f32 v[102:103], v[102:103], v[190:191], v[226:227]
	v_pk_fma_f32 v[96:97], v[96:97], v[192:193], v[228:229]
	v_pk_fma_f32 v[98:99], v[98:99], v[194:195], v[230:231]
	v_cvt_pk_bf16_f32 v100, v100, v101
	v_cvt_pk_bf16_f32 v101, v102, v103
	v_cvt_pk_bf16_f32 v102, v96, v97
	v_cvt_pk_bf16_f32 v103, v98, v99
	global_store_dwordx4 v205, v[100:103], s[28:29] offset:256
	v_add_lshl_u32 v182, v158, v204, 2
	global_load_dwordx4 v[224:227], v182, s[38:39] offset:512
	global_load_dwordx4 v[228:231], v182, s[38:39] offset:528
	s_waitcnt vmcnt(14)
	v_pk_fma_f32 v[92:93], v[92:93], v[174:175], v[232:233]
	v_pk_fma_f32 v[94:95], v[94:95], v[176:177], v[234:235]
	v_pk_fma_f32 v[88:89], v[88:89], v[178:179], v[236:237]
	v_pk_fma_f32 v[90:91], v[90:91], v[180:181], v[238:239]
	v_cvt_pk_bf16_f32 v92, v92, v93
	v_cvt_pk_bf16_f32 v93, v94, v95
	v_cvt_pk_bf16_f32 v94, v88, v89
	v_cvt_pk_bf16_f32 v95, v90, v91
	v_add_lshl_u32 v205, v154, v204, 1
	global_store_dwordx4 v205, v[92:95], s[28:29]
	v_add_lshl_u32 v183, v160, v204, 2
	global_load_dwordx4 v[232:235], v183, s[38:39]
	global_load_dwordx4 v[236:239], v183, s[38:39] offset:16
	s_waitcnt vmcnt(15)
	v_pk_fma_f32 v[84:85], v[84:85], v[188:189], v[240:241]
	v_pk_fma_f32 v[86:87], v[86:87], v[190:191], v[242:243]
	v_pk_fma_f32 v[80:81], v[80:81], v[192:193], v[244:245]
	v_pk_fma_f32 v[82:83], v[82:83], v[194:195], v[246:247]
	v_cvt_pk_bf16_f32 v84, v84, v85
	v_cvt_pk_bf16_f32 v85, v86, v87
	v_cvt_pk_bf16_f32 v86, v80, v81
	v_cvt_pk_bf16_f32 v87, v82, v83
	global_store_dwordx4 v205, v[84:87], s[28:29] offset:256
	v_add_lshl_u32 v182, v160, v204, 2
	global_load_dwordx4 v[240:243], v182, s[38:39] offset:512
	global_load_dwordx4 v[244:247], v182, s[38:39] offset:528
	s_waitcnt vmcnt(15)
; __device__ __forceinline__ unsigned cvt_pk_bf16(float lo, float hi) { unsigned r; asm("v_cvt_pk_bf16_f32 %0, %1, %2" : "=v"(r) : "v"(lo), "v"(hi)); return r; }
;     __device__ __forceinline__ void operator()(const Acc& acc, const Unit& u, int wr, int wc, int fr, int fq) const {
;     ...
;             for (int m = 0; m < 4; ++m) { const size_t off = (size_t)(r0 + ai * 128 + m * 16) * D + col0;
; #pragma unroll
;                 for (int bj = 0; bj < 2; ++bj) { const size_t o2 = off + bj * 128; f32x4 s0, s1;
;                     if (SRC32) { s0 = *(const f32x4*)(sp32 + o2); s1 = *(const f32x4*)(sp32 + o2 + 4); }
;                     else { const u32x4 q = *(const u32x4*)(sp16 + o2); s0 = (f32x4){bf2f(q.x & 0xffffu), bf2f(q.x >> 16), bf2f(q.y & 0xffffu), bf2f(q.y >> 16)}; s1 = (f32x4){bf2f(q.z & 0xffffu), bf2f(q.z >> 16), bf2f(q.w & 0xffffu), bf2f(q.w >> 16)}; }
;                     const f32x4 v0 = s0 + gv[bj][0] * acc[ai][bj][m][0], v1 = s1 + gv[bj][1] * acc[ai][bj][m][1];
;                     if (DST32) { *(f32x4*)(dp32 + o2) = v0; *(f32x4*)(dp32 + o2 + 4) = v1; }
;                     else { u32x4 w; w.x = cvt_pk_bf16(v0.x, v0.y); w.y = cvt_pk_bf16(v0.z, v0.w); w.z = cvt_pk_bf16(v1.x, v1.y); w.w = cvt_pk_bf16(v1.z, v1.w); *(u32x4*)(dp16 + o2) = w; } } }
	v_pk_fma_f32 v[76:77], v[76:77], v[174:175], v[196:197]
	v_pk_fma_f32 v[78:79], v[78:79], v[176:177], v[198:199]
	v_pk_fma_f32 v[72:73], v[72:73], v[178:179], v[200:201]
	v_pk_fma_f32 v[74:75], v[74:75], v[180:181], v[202:203]
	v_cvt_pk_bf16_f32 v76, v76, v77
	v_cvt_pk_bf16_f32 v77, v78, v79
	v_cvt_pk_bf16_f32 v78, v72, v73
	v_cvt_pk_bf16_f32 v79, v74, v75
	v_add_lshl_u32 v205, v156, v204, 1
	global_store_dwordx4 v205, v[76:79], s[28:29]
	v_add_lshl_u32 v183, v162, v204, 2
	global_load_dwordx4 v[196:199], v183, s[38:39]
	global_load_dwordx4 v[200:203], v183, s[38:39] offset:16
	s_waitcnt vmcnt(15)
	v_pk_fma_f32 v[68:69], v[68:69], v[188:189], v[208:209]
	v_pk_fma_f32 v[70:71], v[70:71], v[190:191], v[210:211]
	v_pk_fma_f32 v[64:65], v[64:65], v[192:193], v[212:213]
	v_pk_fma_f32 v[66:67], v[66:67], v[194:195], v[214:215]
	v_cvt_pk_bf16_f32 v68, v68, v69
	v_cvt_pk_bf16_f32 v69, v70, v71
	v_cvt_pk_bf16_f32 v70, v64, v65
	v_cvt_pk_bf16_f32 v71, v66, v67
	global_store_dwordx4 v205, v[68:71], s[28:29] offset:256
	v_add_lshl_u32 v182, v162, v204, 2
	global_load_dwordx4 v[208:211], v182, s[38:39] offset:512
	global_load_dwordx4 v[212:215], v182, s[38:39] offset:528
	s_waitcnt vmcnt(15)
	v_pk_fma_f32 v[60:61], v[60:61], v[174:175], v[216:217]
	v_pk_fma_f32 v[62:63], v[62:63], v[176:177], v[218:219]
	v_pk_fma_f32 v[56:57], v[56:57], v[178:179], v[220:221]
	v_pk_fma_f32 v[58:59], v[58:59], v[180:181], v[222:223]
	v_cvt_pk_bf16_f32 v60, v60, v61
	v_cvt_pk_bf16_f32 v61, v62, v63
	v_cvt_pk_bf16_f32 v62, v56, v57
	v_cvt_pk_bf16_f32 v63, v58, v59
	v_add_lshl_u32 v205, v158, v204, 1
	global_store_dwordx4 v205, v[60:63], s[28:29]
	v_add_lshl_u32 v183, v164, v204, 2
	global_load_dwordx4 v[216:219], v183, s[38:39]
	global_load_dwordx4 v[220:223], v183, s[38:39] offset:16
	s_waitcnt vmcnt(15)
	v_pk_fma_f32 v[52:53], v[52:53], v[188:189], v[224:225]
	v_pk_fma_f32 v[54:55], v[54:55], v[190:191], v[226:227]
	v_pk_fma_f32 v[48:49], v[48:49], v[192:193], v[228:229]
	v_pk_fma_f32 v[50:51], v[50:51], v[194:195], v[230:231]
	v_cvt_pk_bf16_f32 v52, v52, v53
	v_cvt_pk_bf16_f32 v53, v54, v55
	v_cvt_pk_bf16_f32 v54, v48, v49
	v_cvt_pk_bf16_f32 v55, v50, v51
	global_store_dwordx4 v205, v[52:55], s[28:29] offset:256
	v_add_lshl_u32 v182, v164, v204, 2
	global_load_dwordx4 v[224:227], v182, s[38:39] offset:512
	global_load_dwordx4 v[228:231], v182, s[38:39] offset:528
	s_waitcnt vmcnt(15)
	v_pk_fma_f32 v[44:45], v[44:45], v[174:175], v[232:233]
	v_pk_fma_f32 v[46:47], v[46:47], v[176:177], v[234:235]
	v_pk_fma_f32 v[40:41], v[40:41], v[178:179], v[236:237]
	v_pk_fma_f32 v[42:43], v[42:43], v[180:181], v[238:239]
	v_cvt_pk_bf16_f32 v44, v44, v45
	v_cvt_pk_bf16_f32 v45, v46, v47
	v_cvt_pk_bf16_f32 v46, v40, v41
	v_cvt_pk_bf16_f32 v47, v42, v43
	v_add_lshl_u32 v205, v160, v204, 1
	global_store_dwordx4 v205, v[44:47], s[28:29]
	s_waitcnt vmcnt(13)
	v_pk_fma_f32 v[36:37], v[36:37], v[188:189], v[240:241]
	v_pk_fma_f32 v[38:39], v[38:39], v[190:191], v[242:243]
	v_pk_fma_f32 v[32:33], v[32:33], v[192:193], v[244:245]
	v_pk_fma_f32 v[34:35], v[34:35], v[194:195], v[246:247]
	v_cvt_pk_bf16_f32 v36, v36, v37
	v_cvt_pk_bf16_f32 v37, v38, v39
	v_cvt_pk_bf16_f32 v38, v32, v33
	v_cvt_pk_bf16_f32 v39, v34, v35
	global_store_dwordx4 v205, v[36:39], s[28:29] offset:256
	s_waitcnt vmcnt(11)
	v_pk_fma_f32 v[28:29], v[28:29], v[174:175], v[196:197]
	v_pk_fma_f32 v[30:31], v[30:31], v[176:177], v[198:199]
	v_pk_fma_f32 v[24:25], v[24:25], v[178:179], v[200:201]
	v_pk_fma_f32 v[26:27], v[26:27], v[180:181], v[202:203]
	v_cvt_pk_bf16_f32 v28, v28, v29
	v_cvt_pk_bf16_f32 v29, v30, v31
	v_cvt_pk_bf16_f32 v30, v24, v25
	v_cvt_pk_bf16_f32 v31, v26, v27
	v_add_lshl_u32 v205, v162, v204, 1
	global_store_dwordx4 v205, v[28:31], s[28:29]
	s_waitcnt vmcnt(9)
	v_pk_fma_f32 v[20:21], v[20:21], v[188:189], v[208:209]
	v_pk_fma_f32 v[22:23], v[22:23], v[190:191], v[210:211]
	v_pk_fma_f32 v[16:17], v[16:17], v[192:193], v[212:213]
	v_pk_fma_f32 v[18:19], v[18:19], v[194:195], v[214:215]
	v_cvt_pk_bf16_f32 v20, v20, v21
	v_cvt_pk_bf16_f32 v21, v22, v23
	v_cvt_pk_bf16_f32 v22, v16, v17
	v_cvt_pk_bf16_f32 v23, v18, v19
	global_store_dwordx4 v205, v[20:23], s[28:29] offset:256
	s_waitcnt vmcnt(7)
	v_pk_fma_f32 v[12:13], v[12:13], v[174:175], v[216:217]
	v_pk_fma_f32 v[14:15], v[14:15], v[176:177], v[218:219]
	v_pk_fma_f32 v[8:9], v[8:9], v[178:179], v[220:221]
	v_pk_fma_f32 v[10:11], v[10:11], v[180:181], v[222:223]
	v_cvt_pk_bf16_f32 v12, v12, v13
	v_cvt_pk_bf16_f32 v13, v14, v15
	v_cvt_pk_bf16_f32 v14, v8, v9
	v_cvt_pk_bf16_f32 v15, v10, v11
	v_add_lshl_u32 v205, v164, v204, 1
	global_store_dwordx4 v205, v[12:15], s[28:29]
	s_waitcnt vmcnt(5)
	v_pk_fma_f32 v[4:5], v[4:5], v[188:189], v[224:225]
	v_pk_fma_f32 v[6:7], v[6:7], v[190:191], v[226:227]
	v_pk_fma_f32 v[0:1], v[0:1], v[192:193], v[228:229]
	v_pk_fma_f32 v[2:3], v[2:3], v[194:195], v[230:231]
	v_cvt_pk_bf16_f32 v4, v4, v5
	v_cvt_pk_bf16_f32 v5, v6, v7
	v_cvt_pk_bf16_f32 v6, v0, v1
	v_cvt_pk_bf16_f32 v7, v2, v3
	global_store_dwordx4 v205, v[4:7], s[28:29] offset:256
	s_andn2_b64 vcc, exec, s[4:5]
	s_mov_b64 s[4:5], -1
	s_cbranch_vccnz .LBB0_335
	s_branch .LBB0_362

; __device__ __forceinline__ unsigned cvt_pk_bf16(float lo, float hi) { unsigned r; asm("v_cvt_pk_bf16_f32 %0, %1, %2" : "=v"(r) : "v"(lo), "v"(hi)); return r; }
; __device__ __forceinline__ float fast_sigmoid(float x) { return __builtin_amdgcn_rcpf(1.0f + __builtin_amdgcn_exp2f(-x * LOG2E)); }
;     __device__ __forceinline__ void operator()(const Acc& acc, const Unit& u, int wr, int wc, int fr, int fq) const {
;         const int row0 = u.pm * 256 + wr * 64 + fr, col0 = u.pn * 256 + wc * 32 + 8 * fq;
; #pragma unroll
;         for (int ai = 0; ai < 2; ++ai)
; #pragma unroll
;             for (int m = 0; m < 4; ++m) { const int row = row0 + ai * 128 + m * 16;
; #pragma unroll
;                 for (int bj = 0; bj < 2; ++bj) { const int col = col0 + bj * 128; const u32x4 gw = *(const u32x4*)(G + ((size_t)(col >> 4) * MX + row) * 16 + (col & 15)); const f32x4 a = acc[ai][bj][m][0], b = acc[ai][bj][m][1];
;                     u32x4 w; w.x = cvt_pk_bf16(bf2f(gw.x & 0xffffu) * fast_sigmoid(a[0]), bf2f(gw.x >> 16) * fast_sigmoid(a[1])); w.y = cvt_pk_bf16(bf2f(gw.y & 0xffffu) * fast_sigmoid(a[2]), bf2f(gw.y >> 16) * fast_sigmoid(a[3]));
;                     w.z = cvt_pk_bf16(bf2f(gw.z & 0xffffu) * fast_sigmoid(b[0]), bf2f(gw.z >> 16) * fast_sigmoid(b[1])); w.w = cvt_pk_bf16(bf2f(gw.w & 0xffffu) * fast_sigmoid(b[2]), bf2f(gw.w >> 16) * fast_sigmoid(b[3]));
.LBB0_845:
	v_lshl_or_b32 v216, s34, 8, v152
	v_lshrrev_b32_e32 v217, 4, v216
	v_lshlrev_b32_e32 v217, 20, v217
	v_lshl_add_u32 v218, s40, 8, v150
	v_lshl_add_u32 v217, v218, 5, v217
	v_add_u32_e32 v217, v217, v136
	v_add_u32_e32 v219, 0x800000, v217
	v_lshlrev_b32_e32 v218, 11, v218
	v_lshl_add_u32 v218, v216, 1, v218
	s_mov_b32 vcc_lo, 0xbfb8aa3b
	s_mov_b32 vcc_hi, 0xbfb8aa3b
	global_load_dwordx4 v[156:159], v217, s[0:1]
	global_load_dwordx4 v[160:163], v219, s[0:1]
	global_load_dwordx4 v[164:167], v217, s[0:1] offset:512
	global_load_dwordx4 v[168:171], v219, s[0:1] offset:512
	global_load_dwordx4 v[172:175], v217, s[0:1] offset:1024
	global_load_dwordx4 v[176:179], v219, s[0:1] offset:1024
	global_load_dwordx4 v[180:183], v217, s[0:1] offset:1536
	global_load_dwordx4 v[184:187], v219, s[0:1] offset:1536
	v_add_u32_e32 v217, 0x1000, v217
	v_add_u32_e32 v219, 0x1000, v219
	global_load_dwordx4 v[188:191], v217, s[0:1]
	global_load_dwordx4 v[192:195], v219, s[0:1]
	global_load_dwordx4 v[196:199], v217, s[0:1] offset:512
	global_load_dwordx4 v[200:203], v219, s[0:1] offset:512
	s_waitcnt vmcnt(11)
	v_lshlrev_b32_e32 v208, 16, v156
	v_and_b32_e32 v209, 0xffff0000, v156
	v_lshlrev_b32_e32 v210, 16, v157
	v_and_b32_e32 v211, 0xffff0000, v157
	v_lshlrev_b32_e32 v212, 16, v158
	v_and_b32_e32 v213, 0xffff0000, v158
	v_lshlrev_b32_e32 v214, 16, v159
	v_and_b32_e32 v215, 0xffff0000, v159
	v_pk_mul_f32 v[146:147], v[124:125], vcc
	v_pk_mul_f32 v[148:149], v[126:127], vcc
	v_exp_f32_e32 v146, v146
	v_exp_f32_e32 v147, v147
	v_exp_f32_e32 v148, v148
	v_exp_f32_e32 v149, v149
	v_pk_add_f32 v[146:147], v[146:147], 1.0 op_sel_hi:[1,0]
	v_pk_add_f32 v[148:149], v[148:149], 1.0 op_sel_hi:[1,0]
	v_rcp_f32_e32 v146, v146
	v_rcp_f32_e32 v147, v147
	v_rcp_f32_e32 v148, v148
	v_rcp_f32_e32 v149, v149
	v_pk_mul_f32 v[124:125], v[146:147], v[208:209]
	v_pk_mul_f32 v[126:127], v[148:149], v[210:211]
	v_pk_mul_f32 v[146:147], v[120:121], vcc
	v_pk_mul_f32 v[148:149], v[122:123], vcc
	v_exp_f32_e32 v146, v146
	v_exp_f32_e32 v147, v147
	v_exp_f32_e32 v148, v148
	v_exp_f32_e32 v149, v149
	v_pk_add_f32 v[146:147], v[146:147], 1.0 op_sel_hi:[1,0]
	v_pk_add_f32 v[148:149], v[148:149], 1.0 op_sel_hi:[1,0]
	v_rcp_f32_e32 v146, v146
	v_rcp_f32_e32 v147, v147
	v_rcp_f32_e32 v148, v148
	v_rcp_f32_e32 v149, v149
	v_pk_mul_f32 v[120:121], v[146:147], v[212:213]
	v_pk_mul_f32 v[122:123], v[148:149], v[214:215]
	v_cvt_pk_bf16_f32 v124, v124, v125
	v_cvt_pk_bf16_f32 v125, v126, v127
	v_cvt_pk_bf16_f32 v126, v120, v121
	v_cvt_pk_bf16_f32 v127, v122, v123
	v_mov_b32_e32 v216, v218
	global_store_dwordx4 v216, v[124:127], s[6:7] offset:1024
	s_waitcnt vmcnt(11)
	v_lshlrev_b32_e32 v208, 16, v160
	v_and_b32_e32 v209, 0xffff0000, v160
	v_lshlrev_b32_e32 v210, 16, v161
	v_and_b32_e32 v211, 0xffff0000, v161
	v_lshlrev_b32_e32 v212, 16, v162
	v_and_b32_e32 v213, 0xffff0000, v162
	v_lshlrev_b32_e32 v214, 16, v163
	v_and_b32_e32 v215, 0xffff0000, v163
	v_pk_mul_f32 v[146:147], v[116:117], vcc
	v_pk_mul_f32 v[148:149], v[118:119], vcc
	v_exp_f32_e32 v146, v146
	v_exp_f32_e32 v147, v147
	v_exp_f32_e32 v148, v148
	v_exp_f32_e32 v149, v149
	v_pk_add_f32 v[146:147], v[146:147], 1.0 op_sel_hi:[1,0]
	v_pk_add_f32 v[148:149], v[148:149], 1.0 op_sel_hi:[1,0]
	v_rcp_f32_e32 v146, v146
	v_rcp_f32_e32 v147, v147
	v_rcp_f32_e32 v148, v148
	v_rcp_f32_e32 v149, v149
	v_pk_mul_f32 v[116:117], v[146:147], v[208:209]
	v_pk_mul_f32 v[118:119], v[148:149], v[210:211]
	v_pk_mul_f32 v[146:147], v[112:113], vcc
	v_pk_mul_f32 v[148:149], v[114:115], vcc
	v_exp_f32_e32 v146, v146
	v_exp_f32_e32 v147, v147
	v_exp_f32_e32 v148, v148
	v_exp_f32_e32 v149, v149
	v_pk_add_f32 v[146:147], v[146:147], 1.0 op_sel_hi:[1,0]
	v_pk_add_f32 v[148:149], v[148:149], 1.0 op_sel_hi:[1,0]
	v_rcp_f32_e32 v146, v146
	v_rcp_f32_e32 v147, v147
	v_rcp_f32_e32 v148, v148
	v_rcp_f32_e32 v149, v149
	v_pk_mul_f32 v[112:113], v[146:147], v[212:213]
	v_pk_mul_f32 v[114:115], v[148:149], v[214:215]
	v_cvt_pk_bf16_f32 v116, v116, v117
	v_cvt_pk_bf16_f32 v117, v118, v119
	v_cvt_pk_bf16_f32 v118, v112, v113
	v_cvt_pk_bf16_f32 v119, v114, v115
	global_store_dwordx4 v216, v[116:119], s[6:7] offset:1280
	s_waitcnt vmcnt(11)
	v_lshlrev_b32_e32 v208, 16, v164
	v_and_b32_e32 v209, 0xffff0000, v164
	v_lshlrev_b32_e32 v210, 16, v165
	v_and_b32_e32 v211, 0xffff0000, v165
	v_lshlrev_b32_e32 v212, 16, v166
	v_and_b32_e32 v213, 0xffff0000, v166
	v_lshlrev_b32_e32 v214, 16, v167
	v_and_b32_e32 v215, 0xffff0000, v167
	v_pk_mul_f32 v[146:147], v[108:109], vcc
	v_pk_mul_f32 v[148:149], v[110:111], vcc
	v_exp_f32_e32 v146, v146
	v_exp_f32_e32 v147, v147
	v_exp_f32_e32 v148, v148
	v_exp_f32_e32 v149, v149
	v_pk_add_f32 v[146:147], v[146:147], 1.0 op_sel_hi:[1,0]
	v_pk_add_f32 v[148:149], v[148:149], 1.0 op_sel_hi:[1,0]
	v_rcp_f32_e32 v146, v146
	v_rcp_f32_e32 v147, v147
	v_rcp_f32_e32 v148, v148
	v_rcp_f32_e32 v149, v149
	v_pk_mul_f32 v[108:109], v[146:147], v[208:209]
	v_pk_mul_f32 v[110:111], v[148:149], v[210:211]
	v_pk_mul_f32 v[146:147], v[104:105], vcc
	v_pk_mul_f32 v[148:149], v[106:107], vcc
	v_exp_f32_e32 v146, v146
	v_exp_f32_e32 v147, v147
	v_exp_f32_e32 v148, v148
	v_exp_f32_e32 v149, v149
	v_pk_add_f32 v[146:147], v[146:147], 1.0 op_sel_hi:[1,0]
	v_pk_add_f32 v[148:149], v[148:149], 1.0 op_sel_hi:[1,0]
	v_rcp_f32_e32 v146, v146
	v_rcp_f32_e32 v147, v147
	v_rcp_f32_e32 v148, v148
	v_rcp_f32_e32 v149, v149
	v_pk_mul_f32 v[104:105], v[146:147], v[212:213]
	v_pk_mul_f32 v[106:107], v[148:149], v[214:215]
	v_cvt_pk_bf16_f32 v108, v108, v109
	v_cvt_pk_bf16_f32 v109, v110, v111
	v_cvt_pk_bf16_f32 v110, v104, v105
	v_cvt_pk_bf16_f32 v111, v106, v107
	v_add_u32_e32 v216, 0x8000, v218
	global_store_dwordx4 v216, v[108:111], s[6:7] offset:1024
	s_waitcnt vmcnt(11)
; __device__ __forceinline__ unsigned cvt_pk_bf16(float lo, float hi) { unsigned r; asm("v_cvt_pk_bf16_f32 %0, %1, %2" : "=v"(r) : "v"(lo), "v"(hi)); return r; }
; __device__ __forceinline__ float fast_sigmoid(float x) { return __builtin_amdgcn_rcpf(1.0f + __builtin_amdgcn_exp2f(-x * LOG2E)); }
;     __device__ __forceinline__ void operator()(const Acc& acc, const Unit& u, int wr, int wc, int fr, int fq) const {
;     ...
;                 for (int bj = 0; bj < 2; ++bj) { const int col = col0 + bj * 128; const u32x4 gw = *(const u32x4*)(G + ((size_t)(col >> 4) * MX + row) * 16 + (col & 15)); const f32x4 a = acc[ai][bj][m][0], b = acc[ai][bj][m][1];
;                     u32x4 w; w.x = cvt_pk_bf16(bf2f(gw.x & 0xffffu) * fast_sigmoid(a[0]), bf2f(gw.x >> 16) * fast_sigmoid(a[1])); w.y = cvt_pk_bf16(bf2f(gw.y & 0xffffu) * fast_sigmoid(a[2]), bf2f(gw.y >> 16) * fast_sigmoid(a[3]));
;                     w.z = cvt_pk_bf16(bf2f(gw.z & 0xffffu) * fast_sigmoid(b[0]), bf2f(gw.z >> 16) * fast_sigmoid(b[1])); w.w = cvt_pk_bf16(bf2f(gw.w & 0xffffu) * fast_sigmoid(b[2]), bf2f(gw.w >> 16) * fast_sigmoid(b[3]));
;                     *(u32x4*)(MIX + (size_t)row * 1024 + 512 + col) = w; } }
	v_lshlrev_b32_e32 v208, 16, v168
	v_and_b32_e32 v209, 0xffff0000, v168
	v_lshlrev_b32_e32 v210, 16, v169
	v_and_b32_e32 v211, 0xffff0000, v169
	v_lshlrev_b32_e32 v212, 16, v170
	v_and_b32_e32 v213, 0xffff0000, v170
	v_lshlrev_b32_e32 v214, 16, v171
	v_and_b32_e32 v215, 0xffff0000, v171
	global_load_dwordx4 v[156:159], v217, s[0:1] offset:1024
	global_load_dwordx4 v[160:163], v219, s[0:1] offset:1024
	global_load_dwordx4 v[164:167], v217, s[0:1] offset:1536
	global_load_dwordx4 v[168:171], v219, s[0:1] offset:1536
	v_pk_mul_f32 v[146:147], v[100:101], vcc
	v_pk_mul_f32 v[148:149], v[102:103], vcc
	v_exp_f32_e32 v146, v146
	v_exp_f32_e32 v147, v147
	v_exp_f32_e32 v148, v148
	v_exp_f32_e32 v149, v149
	v_pk_add_f32 v[146:147], v[146:147], 1.0 op_sel_hi:[1,0]
	v_pk_add_f32 v[148:149], v[148:149], 1.0 op_sel_hi:[1,0]
	v_rcp_f32_e32 v146, v146
	v_rcp_f32_e32 v147, v147
	v_rcp_f32_e32 v148, v148
	v_rcp_f32_e32 v149, v149
	v_pk_mul_f32 v[100:101], v[146:147], v[208:209]
	v_pk_mul_f32 v[102:103], v[148:149], v[210:211]
	v_pk_mul_f32 v[146:147], v[96:97], vcc
	v_pk_mul_f32 v[148:149], v[98:99], vcc
	v_exp_f32_e32 v146, v146
	v_exp_f32_e32 v147, v147
	v_exp_f32_e32 v148, v148
	v_exp_f32_e32 v149, v149
	v_pk_add_f32 v[146:147], v[146:147], 1.0 op_sel_hi:[1,0]
	v_pk_add_f32 v[148:149], v[148:149], 1.0 op_sel_hi:[1,0]
	v_rcp_f32_e32 v146, v146
	v_rcp_f32_e32 v147, v147
	v_rcp_f32_e32 v148, v148
	v_rcp_f32_e32 v149, v149
	v_pk_mul_f32 v[96:97], v[146:147], v[212:213]
	v_pk_mul_f32 v[98:99], v[148:149], v[214:215]
	v_cvt_pk_bf16_f32 v100, v100, v101
	v_cvt_pk_bf16_f32 v101, v102, v103
	v_cvt_pk_bf16_f32 v102, v96, v97
	v_cvt_pk_bf16_f32 v103, v98, v99
	global_store_dwordx4 v216, v[100:103], s[6:7] offset:1280
	s_waitcnt vmcnt(15)
	v_lshlrev_b32_e32 v208, 16, v172
	v_and_b32_e32 v209, 0xffff0000, v172
	v_lshlrev_b32_e32 v210, 16, v173
	v_and_b32_e32 v211, 0xffff0000, v173
	v_lshlrev_b32_e32 v212, 16, v174
	v_and_b32_e32 v213, 0xffff0000, v174
	v_lshlrev_b32_e32 v214, 16, v175
	v_and_b32_e32 v215, 0xffff0000, v175
	v_pk_mul_f32 v[146:147], v[92:93], vcc
	v_pk_mul_f32 v[148:149], v[94:95], vcc
	v_exp_f32_e32 v146, v146
	v_exp_f32_e32 v147, v147
	v_exp_f32_e32 v148, v148
	v_exp_f32_e32 v149, v149
	v_pk_add_f32 v[146:147], v[146:147], 1.0 op_sel_hi:[1,0]
	v_pk_add_f32 v[148:149], v[148:149], 1.0 op_sel_hi:[1,0]
	v_rcp_f32_e32 v146, v146
	v_rcp_f32_e32 v147, v147
	v_rcp_f32_e32 v148, v148
	v_rcp_f32_e32 v149, v149
	v_pk_mul_f32 v[92:93], v[146:147], v[208:209]
	v_pk_mul_f32 v[94:95], v[148:149], v[210:211]
	v_pk_mul_f32 v[146:147], v[88:89], vcc
	v_pk_mul_f32 v[148:149], v[90:91], vcc
	v_exp_f32_e32 v146, v146
	v_exp_f32_e32 v147, v147
	v_exp_f32_e32 v148, v148
	v_exp_f32_e32 v149, v149
	v_pk_add_f32 v[146:147], v[146:147], 1.0 op_sel_hi:[1,0]
	v_pk_add_f32 v[148:149], v[148:149], 1.0 op_sel_hi:[1,0]
	v_rcp_f32_e32 v146, v146
	v_rcp_f32_e32 v147, v147
	v_rcp_f32_e32 v148, v148
	v_rcp_f32_e32 v149, v149
	v_pk_mul_f32 v[88:89], v[146:147], v[212:213]
	v_pk_mul_f32 v[90:91], v[148:149], v[214:215]
	v_cvt_pk_bf16_f32 v92, v92, v93
	v_cvt_pk_bf16_f32 v93, v94, v95
	v_cvt_pk_bf16_f32 v94, v88, v89
	v_cvt_pk_bf16_f32 v95, v90, v91
	v_add_u32_e32 v216, 0x10000, v218
	global_store_dwordx4 v216, v[92:95], s[6:7] offset:1024
	s_waitcnt vmcnt(15)
	v_lshlrev_b32_e32 v208, 16, v176
	v_and_b32_e32 v209, 0xffff0000, v176
	v_lshlrev_b32_e32 v210, 16, v177
	v_and_b32_e32 v211, 0xffff0000, v177
	v_lshlrev_b32_e32 v212, 16, v178
	v_and_b32_e32 v213, 0xffff0000, v178
	v_lshlrev_b32_e32 v214, 16, v179
	v_and_b32_e32 v215, 0xffff0000, v179
	v_pk_mul_f32 v[146:147], v[84:85], vcc
	v_pk_mul_f32 v[148:149], v[86:87], vcc
	v_exp_f32_e32 v146, v146
	v_exp_f32_e32 v147, v147
	v_exp_f32_e32 v148, v148
	v_exp_f32_e32 v149, v149
	v_pk_add_f32 v[146:147], v[146:147], 1.0 op_sel_hi:[1,0]
	v_pk_add_f32 v[148:149], v[148:149], 1.0 op_sel_hi:[1,0]
	v_rcp_f32_e32 v146, v146
	v_rcp_f32_e32 v147, v147
	v_rcp_f32_e32 v148, v148
	v_rcp_f32_e32 v149, v149
	v_pk_mul_f32 v[84:85], v[146:147], v[208:209]
	v_pk_mul_f32 v[86:87], v[148:149], v[210:211]
	v_pk_mul_f32 v[146:147], v[80:81], vcc
	v_pk_mul_f32 v[148:149], v[82:83], vcc
	v_exp_f32_e32 v146, v146
	v_exp_f32_e32 v147, v147
	v_exp_f32_e32 v148, v148
	v_exp_f32_e32 v149, v149
	v_pk_add_f32 v[146:147], v[146:147], 1.0 op_sel_hi:[1,0]
	v_pk_add_f32 v[148:149], v[148:149], 1.0 op_sel_hi:[1,0]
	v_rcp_f32_e32 v146, v146
	v_rcp_f32_e32 v147, v147
	v_rcp_f32_e32 v148, v148
	v_rcp_f32_e32 v149, v149
	v_pk_mul_f32 v[80:81], v[146:147], v[212:213]
	v_pk_mul_f32 v[82:83], v[148:149], v[214:215]
	v_cvt_pk_bf16_f32 v84, v84, v85
	v_cvt_pk_bf16_f32 v85, v86, v87
	v_cvt_pk_bf16_f32 v86, v80, v81
	v_cvt_pk_bf16_f32 v87, v82, v83
	global_store_dwordx4 v216, v[84:87], s[6:7] offset:1280
	s_waitcnt vmcnt(15)
	v_lshlrev_b32_e32 v208, 16, v180
	v_and_b32_e32 v209, 0xffff0000, v180
	v_lshlrev_b32_e32 v210, 16, v181
	v_and_b32_e32 v211, 0xffff0000, v181
	v_lshlrev_b32_e32 v212, 16, v182
	v_and_b32_e32 v213, 0xffff0000, v182
	v_lshlrev_b32_e32 v214, 16, v183
	v_and_b32_e32 v215, 0xffff0000, v183
	v_pk_mul_f32 v[146:147], v[76:77], vcc
	v_pk_mul_f32 v[148:149], v[78:79], vcc
	v_exp_f32_e32 v146, v146
	v_exp_f32_e32 v147, v147
	v_exp_f32_e32 v148, v148
	v_exp_f32_e32 v149, v149
	v_pk_add_f32 v[146:147], v[146:147], 1.0 op_sel_hi:[1,0]
	v_pk_add_f32 v[148:149], v[148:149], 1.0 op_sel_hi:[1,0]
	v_rcp_f32_e32 v146, v146
	v_rcp_f32_e32 v147, v147
	v_rcp_f32_e32 v148, v148
	v_rcp_f32_e32 v149, v149
	v_pk_mul_f32 v[76:77], v[146:147], v[208:209]
	v_pk_mul_f32 v[78:79], v[148:149], v[210:211]
	v_pk_mul_f32 v[146:147], v[72:73], vcc
	v_pk_mul_f32 v[148:149], v[74:75], vcc
	v_exp_f32_e32 v146, v146
	v_exp_f32_e32 v147, v147
	v_exp_f32_e32 v148, v148
	v_exp_f32_e32 v149, v149
	v_pk_add_f32 v[146:147], v[146:147], 1.0 op_sel_hi:[1,0]
	v_pk_add_f32 v[148:149], v[148:149], 1.0 op_sel_hi:[1,0]
	v_rcp_f32_e32 v146, v146
	v_rcp_f32_e32 v147, v147
	v_rcp_f32_e32 v148, v148
	v_rcp_f32_e32 v149, v149
	v_pk_mul_f32 v[72:73], v[146:147], v[212:213]
	v_pk_mul_f32 v[74:75], v[148:149], v[214:215]
	v_cvt_pk_bf16_f32 v76, v76, v77
	v_cvt_pk_bf16_f32 v77, v78, v79
	v_cvt_pk_bf16_f32 v78, v72, v73
	v_cvt_pk_bf16_f32 v79, v74, v75
	v_add_u32_e32 v216, 0x18000, v218
	global_store_dwordx4 v216, v[76:79], s[6:7] offset:1024
	s_waitcnt vmcnt(15)
; __device__ __forceinline__ unsigned cvt_pk_bf16(float lo, float hi) { unsigned r; asm("v_cvt_pk_bf16_f32 %0, %1, %2" : "=v"(r) : "v"(lo), "v"(hi)); return r; }
; __device__ __forceinline__ float fast_sigmoid(float x) { return __builtin_amdgcn_rcpf(1.0f + __builtin_amdgcn_exp2f(-x * LOG2E)); }
;     __device__ __forceinline__ void operator()(const Acc& acc, const Unit& u, int wr, int wc, int fr, int fq) const {
;     ...
;                 for (int bj = 0; bj < 2; ++bj) { const int col = col0 + bj * 128; const u32x4 gw = *(const u32x4*)(G + ((size_t)(col >> 4) * MX + row) * 16 + (col & 15)); const f32x4 a = acc[ai][bj][m][0], b = acc[ai][bj][m][1];
;                     u32x4 w; w.x = cvt_pk_bf16(bf2f(gw.x & 0xffffu) * fast_sigmoid(a[0]), bf2f(gw.x >> 16) * fast_sigmoid(a[1])); w.y = cvt_pk_bf16(bf2f(gw.y & 0xffffu) * fast_sigmoid(a[2]), bf2f(gw.y >> 16) * fast_sigmoid(a[3]));
;                     w.z = cvt_pk_bf16(bf2f(gw.z & 0xffffu) * fast_sigmoid(b[0]), bf2f(gw.z >> 16) * fast_sigmoid(b[1])); w.w = cvt_pk_bf16(bf2f(gw.w & 0xffffu) * fast_sigmoid(b[2]), bf2f(gw.w >> 16) * fast_sigmoid(b[3]));
;                     *(u32x4*)(MIX + (size_t)row * 1024 + 512 + col) = w; } }
	v_lshlrev_b32_e32 v208, 16, v184
	v_and_b32_e32 v209, 0xffff0000, v184
	v_lshlrev_b32_e32 v210, 16, v185
	v_and_b32_e32 v211, 0xffff0000, v185
	v_lshlrev_b32_e32 v212, 16, v186
	v_and_b32_e32 v213, 0xffff0000, v186
	v_lshlrev_b32_e32 v214, 16, v187
	v_and_b32_e32 v215, 0xffff0000, v187
	v_pk_mul_f32 v[146:147], v[68:69], vcc
	v_pk_mul_f32 v[148:149], v[70:71], vcc
	v_exp_f32_e32 v146, v146
	v_exp_f32_e32 v147, v147
	v_exp_f32_e32 v148, v148
	v_exp_f32_e32 v149, v149
	v_pk_add_f32 v[146:147], v[146:147], 1.0 op_sel_hi:[1,0]
	v_pk_add_f32 v[148:149], v[148:149], 1.0 op_sel_hi:[1,0]
	v_rcp_f32_e32 v146, v146
	v_rcp_f32_e32 v147, v147
	v_rcp_f32_e32 v148, v148
	v_rcp_f32_e32 v149, v149
	v_pk_mul_f32 v[68:69], v[146:147], v[208:209]
	v_pk_mul_f32 v[70:71], v[148:149], v[210:211]
	v_pk_mul_f32 v[146:147], v[64:65], vcc
	v_pk_mul_f32 v[148:149], v[66:67], vcc
	v_exp_f32_e32 v146, v146
	v_exp_f32_e32 v147, v147
	v_exp_f32_e32 v148, v148
	v_exp_f32_e32 v149, v149
	v_pk_add_f32 v[146:147], v[146:147], 1.0 op_sel_hi:[1,0]
	v_pk_add_f32 v[148:149], v[148:149], 1.0 op_sel_hi:[1,0]
	v_rcp_f32_e32 v146, v146
	v_rcp_f32_e32 v147, v147
	v_rcp_f32_e32 v148, v148
	v_rcp_f32_e32 v149, v149
	v_pk_mul_f32 v[64:65], v[146:147], v[212:213]
	v_pk_mul_f32 v[66:67], v[148:149], v[214:215]
	v_cvt_pk_bf16_f32 v68, v68, v69
	v_cvt_pk_bf16_f32 v69, v70, v71
	v_cvt_pk_bf16_f32 v70, v64, v65
	v_cvt_pk_bf16_f32 v71, v66, v67
	global_store_dwordx4 v216, v[68:71], s[6:7] offset:1280
	s_waitcnt vmcnt(15)
	v_lshlrev_b32_e32 v208, 16, v188
	v_and_b32_e32 v209, 0xffff0000, v188
	v_lshlrev_b32_e32 v210, 16, v189
	v_and_b32_e32 v211, 0xffff0000, v189
	v_lshlrev_b32_e32 v212, 16, v190
	v_and_b32_e32 v213, 0xffff0000, v190
	v_lshlrev_b32_e32 v214, 16, v191
	v_and_b32_e32 v215, 0xffff0000, v191
	v_pk_mul_f32 v[146:147], v[60:61], vcc
	v_pk_mul_f32 v[148:149], v[62:63], vcc
	v_exp_f32_e32 v146, v146
	v_exp_f32_e32 v147, v147
	v_exp_f32_e32 v148, v148
	v_exp_f32_e32 v149, v149
	v_pk_add_f32 v[146:147], v[146:147], 1.0 op_sel_hi:[1,0]
	v_pk_add_f32 v[148:149], v[148:149], 1.0 op_sel_hi:[1,0]
	v_rcp_f32_e32 v146, v146
	v_rcp_f32_e32 v147, v147
	v_rcp_f32_e32 v148, v148
	v_rcp_f32_e32 v149, v149
	v_pk_mul_f32 v[60:61], v[146:147], v[208:209]
	v_pk_mul_f32 v[62:63], v[148:149], v[210:211]
	v_pk_mul_f32 v[146:147], v[56:57], vcc
	v_pk_mul_f32 v[148:149], v[58:59], vcc
	v_exp_f32_e32 v146, v146
	v_exp_f32_e32 v147, v147
	v_exp_f32_e32 v148, v148
	v_exp_f32_e32 v149, v149
	v_pk_add_f32 v[146:147], v[146:147], 1.0 op_sel_hi:[1,0]
	v_pk_add_f32 v[148:149], v[148:149], 1.0 op_sel_hi:[1,0]
	v_rcp_f32_e32 v146, v146
	v_rcp_f32_e32 v147, v147
	v_rcp_f32_e32 v148, v148
	v_rcp_f32_e32 v149, v149
	v_pk_mul_f32 v[56:57], v[146:147], v[212:213]
	v_pk_mul_f32 v[58:59], v[148:149], v[214:215]
	v_cvt_pk_bf16_f32 v60, v60, v61
	v_cvt_pk_bf16_f32 v61, v62, v63
	v_cvt_pk_bf16_f32 v62, v56, v57
	v_cvt_pk_bf16_f32 v63, v58, v59
	v_add_u32_e32 v216, 0x40000, v218
	global_store_dwordx4 v216, v[60:63], s[6:7] offset:1024
	s_waitcnt vmcnt(15)
	v_lshlrev_b32_e32 v208, 16, v192
	v_and_b32_e32 v209, 0xffff0000, v192
	v_lshlrev_b32_e32 v210, 16, v193
	v_and_b32_e32 v211, 0xffff0000, v193
	v_lshlrev_b32_e32 v212, 16, v194
	v_and_b32_e32 v213, 0xffff0000, v194
	v_lshlrev_b32_e32 v214, 16, v195
	v_and_b32_e32 v215, 0xffff0000, v195
	v_pk_mul_f32 v[146:147], v[52:53], vcc
	v_pk_mul_f32 v[148:149], v[54:55], vcc
	v_exp_f32_e32 v146, v146
	v_exp_f32_e32 v147, v147
	v_exp_f32_e32 v148, v148
	v_exp_f32_e32 v149, v149
	v_pk_add_f32 v[146:147], v[146:147], 1.0 op_sel_hi:[1,0]
	v_pk_add_f32 v[148:149], v[148:149], 1.0 op_sel_hi:[1,0]
	v_rcp_f32_e32 v146, v146
	v_rcp_f32_e32 v147, v147
	v_rcp_f32_e32 v148, v148
	v_rcp_f32_e32 v149, v149
	v_pk_mul_f32 v[52:53], v[146:147], v[208:209]
	v_pk_mul_f32 v[54:55], v[148:149], v[210:211]
	v_pk_mul_f32 v[146:147], v[48:49], vcc
	v_pk_mul_f32 v[148:149], v[50:51], vcc
	v_exp_f32_e32 v146, v146
	v_exp_f32_e32 v147, v147
	v_exp_f32_e32 v148, v148
	v_exp_f32_e32 v149, v149
	v_pk_add_f32 v[146:147], v[146:147], 1.0 op_sel_hi:[1,0]
	v_pk_add_f32 v[148:149], v[148:149], 1.0 op_sel_hi:[1,0]
	v_rcp_f32_e32 v146, v146
	v_rcp_f32_e32 v147, v147
	v_rcp_f32_e32 v148, v148
	v_rcp_f32_e32 v149, v149
	v_pk_mul_f32 v[48:49], v[146:147], v[212:213]
	v_pk_mul_f32 v[50:51], v[148:149], v[214:215]
	v_cvt_pk_bf16_f32 v52, v52, v53
	v_cvt_pk_bf16_f32 v53, v54, v55
	v_cvt_pk_bf16_f32 v54, v48, v49
	v_cvt_pk_bf16_f32 v55, v50, v51
	global_store_dwordx4 v216, v[52:55], s[6:7] offset:1280
	s_waitcnt vmcnt(15)
	v_lshlrev_b32_e32 v208, 16, v196
	v_and_b32_e32 v209, 0xffff0000, v196
	v_lshlrev_b32_e32 v210, 16, v197
	v_and_b32_e32 v211, 0xffff0000, v197
	v_lshlrev_b32_e32 v212, 16, v198
	v_and_b32_e32 v213, 0xffff0000, v198
	v_lshlrev_b32_e32 v214, 16, v199
	v_and_b32_e32 v215, 0xffff0000, v199
	v_pk_mul_f32 v[146:147], v[44:45], vcc
	v_pk_mul_f32 v[148:149], v[46:47], vcc
	v_exp_f32_e32 v146, v146
	v_exp_f32_e32 v147, v147
	v_exp_f32_e32 v148, v148
	v_exp_f32_e32 v149, v149
	v_pk_add_f32 v[146:147], v[146:147], 1.0 op_sel_hi:[1,0]
	v_pk_add_f32 v[148:149], v[148:149], 1.0 op_sel_hi:[1,0]
	v_rcp_f32_e32 v146, v146
	v_rcp_f32_e32 v147, v147
	v_rcp_f32_e32 v148, v148
	v_rcp_f32_e32 v149, v149
	v_pk_mul_f32 v[44:45], v[146:147], v[208:209]
	v_pk_mul_f32 v[46:47], v[148:149], v[210:211]
	v_pk_mul_f32 v[146:147], v[40:41], vcc
	v_pk_mul_f32 v[148:149], v[42:43], vcc
	v_exp_f32_e32 v146, v146
	v_exp_f32_e32 v147, v147
	v_exp_f32_e32 v148, v148
	v_exp_f32_e32 v149, v149
	v_pk_add_f32 v[146:147], v[146:147], 1.0 op_sel_hi:[1,0]
	v_pk_add_f32 v[148:149], v[148:149], 1.0 op_sel_hi:[1,0]
	v_rcp_f32_e32 v146, v146
	v_rcp_f32_e32 v147, v147
	v_rcp_f32_e32 v148, v148
	v_rcp_f32_e32 v149, v149
	v_pk_mul_f32 v[40:41], v[146:147], v[212:213]
	v_pk_mul_f32 v[42:43], v[148:149], v[214:215]
	v_cvt_pk_bf16_f32 v44, v44, v45
	v_cvt_pk_bf16_f32 v45, v46, v47
	v_cvt_pk_bf16_f32 v46, v40, v41
	v_cvt_pk_bf16_f32 v47, v42, v43
	v_add_u32_e32 v216, 0x48000, v218
	global_store_dwordx4 v216, v[44:47], s[6:7] offset:1024
	s_waitcnt vmcnt(15)
; __device__ __forceinline__ unsigned cvt_pk_bf16(float lo, float hi) { unsigned r; asm("v_cvt_pk_bf16_f32 %0, %1, %2" : "=v"(r) : "v"(lo), "v"(hi)); return r; }
; __device__ __forceinline__ float fast_sigmoid(float x) { return __builtin_amdgcn_rcpf(1.0f + __builtin_amdgcn_exp2f(-x * LOG2E)); }
;     __device__ __forceinline__ void operator()(const Acc& acc, const Unit& u, int wr, int wc, int fr, int fq) const {
;     ...
;                 for (int bj = 0; bj < 2; ++bj) { const int col = col0 + bj * 128; const u32x4 gw = *(const u32x4*)(G + ((size_t)(col >> 4) * MX + row) * 16 + (col & 15)); const f32x4 a = acc[ai][bj][m][0], b = acc[ai][bj][m][1];
;                     u32x4 w; w.x = cvt_pk_bf16(bf2f(gw.x & 0xffffu) * fast_sigmoid(a[0]), bf2f(gw.x >> 16) * fast_sigmoid(a[1])); w.y = cvt_pk_bf16(bf2f(gw.y & 0xffffu) * fast_sigmoid(a[2]), bf2f(gw.y >> 16) * fast_sigmoid(a[3]));
;                     w.z = cvt_pk_bf16(bf2f(gw.z & 0xffffu) * fast_sigmoid(b[0]), bf2f(gw.z >> 16) * fast_sigmoid(b[1])); w.w = cvt_pk_bf16(bf2f(gw.w & 0xffffu) * fast_sigmoid(b[2]), bf2f(gw.w >> 16) * fast_sigmoid(b[3]));
;                     *(u32x4*)(MIX + (size_t)row * 1024 + 512 + col) = w; } }
	v_lshlrev_b32_e32 v208, 16, v200
	v_and_b32_e32 v209, 0xffff0000, v200
	v_lshlrev_b32_e32 v210, 16, v201
	v_and_b32_e32 v211, 0xffff0000, v201
	v_lshlrev_b32_e32 v212, 16, v202
	v_and_b32_e32 v213, 0xffff0000, v202
	v_lshlrev_b32_e32 v214, 16, v203
	v_and_b32_e32 v215, 0xffff0000, v203
	v_pk_mul_f32 v[146:147], v[36:37], vcc
	v_pk_mul_f32 v[148:149], v[38:39], vcc
	v_exp_f32_e32 v146, v146
	v_exp_f32_e32 v147, v147
	v_exp_f32_e32 v148, v148
	v_exp_f32_e32 v149, v149
	v_pk_add_f32 v[146:147], v[146:147], 1.0 op_sel_hi:[1,0]
	v_pk_add_f32 v[148:149], v[148:149], 1.0 op_sel_hi:[1,0]
	v_rcp_f32_e32 v146, v146
	v_rcp_f32_e32 v147, v147
	v_rcp_f32_e32 v148, v148
	v_rcp_f32_e32 v149, v149
	v_pk_mul_f32 v[36:37], v[146:147], v[208:209]
	v_pk_mul_f32 v[38:39], v[148:149], v[210:211]
	v_pk_mul_f32 v[146:147], v[32:33], vcc
	v_pk_mul_f32 v[148:149], v[34:35], vcc
	v_exp_f32_e32 v146, v146
	v_exp_f32_e32 v147, v147
	v_exp_f32_e32 v148, v148
	v_exp_f32_e32 v149, v149
	v_pk_add_f32 v[146:147], v[146:147], 1.0 op_sel_hi:[1,0]
	v_pk_add_f32 v[148:149], v[148:149], 1.0 op_sel_hi:[1,0]
	v_rcp_f32_e32 v146, v146
	v_rcp_f32_e32 v147, v147
	v_rcp_f32_e32 v148, v148
	v_rcp_f32_e32 v149, v149
	v_pk_mul_f32 v[32:33], v[146:147], v[212:213]
	v_pk_mul_f32 v[34:35], v[148:149], v[214:215]
	v_cvt_pk_bf16_f32 v36, v36, v37
	v_cvt_pk_bf16_f32 v37, v38, v39
	v_cvt_pk_bf16_f32 v38, v32, v33
	v_cvt_pk_bf16_f32 v39, v34, v35
	global_store_dwordx4 v216, v[36:39], s[6:7] offset:1280
	s_waitcnt vmcnt(12)
	v_lshlrev_b32_e32 v208, 16, v156
	v_and_b32_e32 v209, 0xffff0000, v156
	v_lshlrev_b32_e32 v210, 16, v157
	v_and_b32_e32 v211, 0xffff0000, v157
	v_lshlrev_b32_e32 v212, 16, v158
	v_and_b32_e32 v213, 0xffff0000, v158
	v_lshlrev_b32_e32 v214, 16, v159
	v_and_b32_e32 v215, 0xffff0000, v159
	v_pk_mul_f32 v[146:147], v[28:29], vcc
	v_pk_mul_f32 v[148:149], v[30:31], vcc
	v_exp_f32_e32 v146, v146
	v_exp_f32_e32 v147, v147
	v_exp_f32_e32 v148, v148
	v_exp_f32_e32 v149, v149
	v_pk_add_f32 v[146:147], v[146:147], 1.0 op_sel_hi:[1,0]
	v_pk_add_f32 v[148:149], v[148:149], 1.0 op_sel_hi:[1,0]
	v_rcp_f32_e32 v146, v146
	v_rcp_f32_e32 v147, v147
	v_rcp_f32_e32 v148, v148
	v_rcp_f32_e32 v149, v149
	v_pk_mul_f32 v[28:29], v[146:147], v[208:209]
	v_pk_mul_f32 v[30:31], v[148:149], v[210:211]
	v_pk_mul_f32 v[146:147], v[24:25], vcc
	v_pk_mul_f32 v[148:149], v[26:27], vcc
	v_exp_f32_e32 v146, v146
	v_exp_f32_e32 v147, v147
	v_exp_f32_e32 v148, v148
	v_exp_f32_e32 v149, v149
	v_pk_add_f32 v[146:147], v[146:147], 1.0 op_sel_hi:[1,0]
	v_pk_add_f32 v[148:149], v[148:149], 1.0 op_sel_hi:[1,0]
	v_rcp_f32_e32 v146, v146
	v_rcp_f32_e32 v147, v147
	v_rcp_f32_e32 v148, v148
	v_rcp_f32_e32 v149, v149
	v_pk_mul_f32 v[24:25], v[146:147], v[212:213]
	v_pk_mul_f32 v[26:27], v[148:149], v[214:215]
	v_cvt_pk_bf16_f32 v28, v28, v29
	v_cvt_pk_bf16_f32 v29, v30, v31
	v_cvt_pk_bf16_f32 v30, v24, v25
	v_cvt_pk_bf16_f32 v31, v26, v27
	v_add_u32_e32 v216, 0x50000, v218
	global_store_dwordx4 v216, v[28:31], s[6:7] offset:1024
	s_waitcnt vmcnt(12)
	v_lshlrev_b32_e32 v208, 16, v160
	v_and_b32_e32 v209, 0xffff0000, v160
	v_lshlrev_b32_e32 v210, 16, v161
	v_and_b32_e32 v211, 0xffff0000, v161
	v_lshlrev_b32_e32 v212, 16, v162
	v_and_b32_e32 v213, 0xffff0000, v162
	v_lshlrev_b32_e32 v214, 16, v163
	v_and_b32_e32 v215, 0xffff0000, v163
	v_pk_mul_f32 v[146:147], v[20:21], vcc
	v_pk_mul_f32 v[148:149], v[22:23], vcc
	v_exp_f32_e32 v146, v146
	v_exp_f32_e32 v147, v147
	v_exp_f32_e32 v148, v148
	v_exp_f32_e32 v149, v149
	v_pk_add_f32 v[146:147], v[146:147], 1.0 op_sel_hi:[1,0]
	v_pk_add_f32 v[148:149], v[148:149], 1.0 op_sel_hi:[1,0]
	v_rcp_f32_e32 v146, v146
	v_rcp_f32_e32 v147, v147
	v_rcp_f32_e32 v148, v148
	v_rcp_f32_e32 v149, v149
	v_pk_mul_f32 v[20:21], v[146:147], v[208:209]
	v_pk_mul_f32 v[22:23], v[148:149], v[210:211]
	v_pk_mul_f32 v[146:147], v[16:17], vcc
	v_pk_mul_f32 v[148:149], v[18:19], vcc
	v_exp_f32_e32 v146, v146
	v_exp_f32_e32 v147, v147
	v_exp_f32_e32 v148, v148
	v_exp_f32_e32 v149, v149
	v_pk_add_f32 v[146:147], v[146:147], 1.0 op_sel_hi:[1,0]
	v_pk_add_f32 v[148:149], v[148:149], 1.0 op_sel_hi:[1,0]
	v_rcp_f32_e32 v146, v146
	v_rcp_f32_e32 v147, v147
	v_rcp_f32_e32 v148, v148
	v_rcp_f32_e32 v149, v149
	v_pk_mul_f32 v[16:17], v[146:147], v[212:213]
	v_pk_mul_f32 v[18:19], v[148:149], v[214:215]
	v_cvt_pk_bf16_f32 v20, v20, v21
	v_cvt_pk_bf16_f32 v21, v22, v23
	v_cvt_pk_bf16_f32 v22, v16, v17
	v_cvt_pk_bf16_f32 v23, v18, v19
	global_store_dwordx4 v216, v[20:23], s[6:7] offset:1280
	s_waitcnt vmcnt(12)
; __device__ __forceinline__ unsigned cvt_pk_bf16(float lo, float hi) { unsigned r; asm("v_cvt_pk_bf16_f32 %0, %1, %2" : "=v"(r) : "v"(lo), "v"(hi)); return r; }
; __device__ __forceinline__ float fast_sigmoid(float x) { return __builtin_amdgcn_rcpf(1.0f + __builtin_amdgcn_exp2f(-x * LOG2E)); }
;     __device__ __forceinline__ void operator()(const Acc& acc, const Unit& u, int wr, int wc, int fr, int fq) const {
;     ...
;                 for (int bj = 0; bj < 2; ++bj) { const int col = col0 + bj * 128; const u32x4 gw = *(const u32x4*)(G + ((size_t)(col >> 4) * MX + row) * 16 + (col & 15)); const f32x4 a = acc[ai][bj][m][0], b = acc[ai][bj][m][1];
;                     u32x4 w; w.x = cvt_pk_bf16(bf2f(gw.x & 0xffffu) * fast_sigmoid(a[0]), bf2f(gw.x >> 16) * fast_sigmoid(a[1])); w.y = cvt_pk_bf16(bf2f(gw.y & 0xffffu) * fast_sigmoid(a[2]), bf2f(gw.y >> 16) * fast_sigmoid(a[3]));
;                     w.z = cvt_pk_bf16(bf2f(gw.z & 0xffffu) * fast_sigmoid(b[0]), bf2f(gw.z >> 16) * fast_sigmoid(b[1])); w.w = cvt_pk_bf16(bf2f(gw.w & 0xffffu) * fast_sigmoid(b[2]), bf2f(gw.w >> 16) * fast_sigmoid(b[3]));
;                     *(u32x4*)(MIX + (size_t)row * 1024 + 512 + col) = w; } }
	v_lshlrev_b32_e32 v208, 16, v164
	v_and_b32_e32 v209, 0xffff0000, v164
	v_lshlrev_b32_e32 v210, 16, v165
	v_and_b32_e32 v211, 0xffff0000, v165
	v_lshlrev_b32_e32 v212, 16, v166
	v_and_b32_e32 v213, 0xffff0000, v166
	v_lshlrev_b32_e32 v214, 16, v167
	v_and_b32_e32 v215, 0xffff0000, v167
	v_pk_mul_f32 v[146:147], v[12:13], vcc
	v_pk_mul_f32 v[148:149], v[14:15], vcc
	v_exp_f32_e32 v146, v146
	v_exp_f32_e32 v147, v147
	v_exp_f32_e32 v148, v148
	v_exp_f32_e32 v149, v149
	v_pk_add_f32 v[146:147], v[146:147], 1.0 op_sel_hi:[1,0]
	v_pk_add_f32 v[148:149], v[148:149], 1.0 op_sel_hi:[1,0]
	v_rcp_f32_e32 v146, v146
	v_rcp_f32_e32 v147, v147
	v_rcp_f32_e32 v148, v148
	v_rcp_f32_e32 v149, v149
	v_pk_mul_f32 v[12:13], v[146:147], v[208:209]
	v_pk_mul_f32 v[14:15], v[148:149], v[210:211]
	v_pk_mul_f32 v[146:147], v[8:9], vcc
	v_pk_mul_f32 v[148:149], v[10:11], vcc
	v_exp_f32_e32 v146, v146
	v_exp_f32_e32 v147, v147
	v_exp_f32_e32 v148, v148
	v_exp_f32_e32 v149, v149
	v_pk_add_f32 v[146:147], v[146:147], 1.0 op_sel_hi:[1,0]
	v_pk_add_f32 v[148:149], v[148:149], 1.0 op_sel_hi:[1,0]
	v_rcp_f32_e32 v146, v146
	v_rcp_f32_e32 v147, v147
	v_rcp_f32_e32 v148, v148
	v_rcp_f32_e32 v149, v149
	v_pk_mul_f32 v[8:9], v[146:147], v[212:213]
	v_pk_mul_f32 v[10:11], v[148:149], v[214:215]
	v_cvt_pk_bf16_f32 v12, v12, v13
	v_cvt_pk_bf16_f32 v13, v14, v15
	v_cvt_pk_bf16_f32 v14, v8, v9
	v_cvt_pk_bf16_f32 v15, v10, v11
	v_add_u32_e32 v216, 0x58000, v218
	global_store_dwordx4 v216, v[12:15], s[6:7] offset:1024
	s_waitcnt vmcnt(12)
	v_lshlrev_b32_e32 v208, 16, v168
	v_and_b32_e32 v209, 0xffff0000, v168
	v_lshlrev_b32_e32 v210, 16, v169
	v_and_b32_e32 v211, 0xffff0000, v169
	v_lshlrev_b32_e32 v212, 16, v170
	v_and_b32_e32 v213, 0xffff0000, v170
	v_lshlrev_b32_e32 v214, 16, v171
	v_and_b32_e32 v215, 0xffff0000, v171
	v_pk_mul_f32 v[146:147], v[4:5], vcc
	v_pk_mul_f32 v[148:149], v[6:7], vcc
	v_exp_f32_e32 v146, v146
	v_exp_f32_e32 v147, v147
	v_exp_f32_e32 v148, v148
	v_exp_f32_e32 v149, v149
	v_pk_add_f32 v[146:147], v[146:147], 1.0 op_sel_hi:[1,0]
	v_pk_add_f32 v[148:149], v[148:149], 1.0 op_sel_hi:[1,0]
	v_rcp_f32_e32 v146, v146
	v_rcp_f32_e32 v147, v147
	v_rcp_f32_e32 v148, v148
	v_rcp_f32_e32 v149, v149
	v_pk_mul_f32 v[4:5], v[146:147], v[208:209]
	v_pk_mul_f32 v[6:7], v[148:149], v[210:211]
	v_pk_mul_f32 v[146:147], v[0:1], vcc
	v_pk_mul_f32 v[148:149], v[2:3], vcc
	v_exp_f32_e32 v146, v146
	v_exp_f32_e32 v147, v147
	v_exp_f32_e32 v148, v148
	v_exp_f32_e32 v149, v149
	v_pk_add_f32 v[146:147], v[146:147], 1.0 op_sel_hi:[1,0]
	v_pk_add_f32 v[148:149], v[148:149], 1.0 op_sel_hi:[1,0]
	v_rcp_f32_e32 v146, v146
	v_rcp_f32_e32 v147, v147
	v_rcp_f32_e32 v148, v148
	v_rcp_f32_e32 v149, v149
	v_pk_mul_f32 v[0:1], v[146:147], v[212:213]
	v_pk_mul_f32 v[2:3], v[148:149], v[214:215]
	v_cvt_pk_bf16_f32 v4, v4, v5
	v_cvt_pk_bf16_f32 v5, v6, v7
	v_cvt_pk_bf16_f32 v6, v0, v1
	v_cvt_pk_bf16_f32 v7, v2, v3
	global_store_dwordx4 v216, v[4:7], s[6:7] offset:1280
	s_andn2_b64 vcc, exec, s[4:5]
	s_mov_b64 s[4:5], -1
	s_cbranch_vccnz .LBB0_834
	s_andn2_b64 vcc, exec, s[8:9]
	s_cbranch_vccnz .LBB0_833
	s_barrier
	s_branch .LBB0_833

; __device__ __forceinline__ unsigned cvt_pk_bf16(float lo, float hi) { unsigned r; asm("v_cvt_pk_bf16_f32 %0, %1, %2" : "=v"(r) : "v"(lo), "v"(hi)); return r; }
;     __device__ __forceinline__ void operator()(const Acc& acc, const Unit& u, int wr, int wc, int fr, int fq) const {
;         const bool isx = u.pm < 128; const int mb = isx ? (u.pm >> 4) : 8;
;         const size_t tile0 = (size_t)(isx ? u.pm : u.pm - 128) * 256 * D;
;         const float* sp32 = (const float*)(isx ? srcx : srcc) + tile0; const bf16_t* sp16 = (const bf16_t*)(isx ? srcx : srcc) + tile0;
;         float* dp32 = (float*)(isx ? dstx : dstc) + tile0; bf16_t* dp16 = (bf16_t*)(isx ? dstx : dstc) + tile0;
;         const int r0 = wr * 64 + fr, col0 = u.pn * 256 + wc * 32 + 8 * fq; const float* gp = gate + (size_t)mb * 9216 + col0;
;         f32x4 gv[2][2];
; #pragma unroll
;         for (int bj = 0; bj < 2; ++bj)
; #pragma unroll
;             for (int n = 0; n < 2; ++n) gv[bj][n] = *(const f32x4*)(gp + bj * 128 + n * 4) * f;
; #pragma unroll
;         for (int ai = 0; ai < 2; ++ai)
; #pragma unroll
;             for (int m = 0; m < 4; ++m) { const size_t off = (size_t)(r0 + ai * 128 + m * 16) * D + col0;
; #pragma unroll
;                 for (int bj = 0; bj < 2; ++bj) { const size_t o2 = off + bj * 128; f32x4 s0, s1;
;                     if (SRC32) { s0 = *(const f32x4*)(sp32 + o2); s1 = *(const f32x4*)(sp32 + o2 + 4); }
;                     else { const u32x4 q = *(const u32x4*)(sp16 + o2); s0 = (f32x4){bf2f(q.x & 0xffffu), bf2f(q.x >> 16), bf2f(q.y & 0xffffu), bf2f(q.y >> 16)}; s1 = (f32x4){bf2f(q.z & 0xffffu), bf2f(q.z >> 16), bf2f(q.w & 0xffffu), bf2f(q.w >> 16)}; }
;                     const f32x4 v0 = s0 + gv[bj][0] * acc[ai][bj][m][0], v1 = s1 + gv[bj][1] * acc[ai][bj][m][1];
;                     if (DST32) { *(f32x4*)(dp32 + o2) = v0; *(f32x4*)(dp32 + o2 + 4) = v1; }
;                     else { u32x4 w; w.x = cvt_pk_bf16(v0.x, v0.y); w.y = cvt_pk_bf16(v0.z, v0.w); w.z = cvt_pk_bf16(v1.x, v1.y); w.w = cvt_pk_bf16(v1.z, v1.w); *(u32x4*)(dp16 + o2) = w; } } }
.LBB0_1742:
	s_add_i32 s23, s38, 0xffffff80
	s_and_b64 s[42:43], s[42:43], exec
	s_cselect_b32 s42, s38, s23
	s_ashr_i32 s43, s42, 31
	v_lshl_or_b32 v172, s39, 8, v175
	s_lshl_b64 s[38:39], s[40:41], 2
	s_add_u32 s38, s50, s38
	s_addc_u32 s39, s51, s39
	s_lshl_b64 s[42:43], s[42:43], 19
	s_add_u32 s40, s86, s42
	s_addc_u32 s41, s87, s43
	v_lshlrev_b32_e32 v184, 2, v172
	global_load_dwordx4 v[128:131], v184, s[38:39]
	global_load_dwordx4 v[124:127], v184, s[38:39] offset:16
	global_load_dwordx4 v[108:111], v184, s[38:39] offset:512
	global_load_dwordx4 v[104:107], v184, s[38:39] offset:528
	s_add_u32 s38, s72, s42
	s_addc_u32 s39, s73, s43
	v_add_lshl_u32 v185, v148, v172, 1
	global_load_dwordx4 v[192:195], v185, s[40:41]
	global_load_dwordx4 v[196:199], v185, s[40:41] offset:256
	v_add_lshl_u32 v184, v150, v172, 1
	global_load_dwordx4 v[200:203], v184, s[40:41]
	global_load_dwordx4 v[208:211], v184, s[40:41] offset:256
	v_add_lshl_u32 v185, v152, v172, 1
	global_load_dwordx4 v[212:215], v185, s[40:41]
	global_load_dwordx4 v[216:219], v185, s[40:41] offset:256
	v_add_lshl_u32 v184, v154, v172, 1
	global_load_dwordx4 v[220:223], v184, s[40:41]
	global_load_dwordx4 v[224:227], v184, s[40:41] offset:256
	v_add_lshl_u32 v185, v156, v172, 1
	global_load_dwordx4 v[228:231], v185, s[40:41]
	global_load_dwordx4 v[238:241], v185, s[40:41] offset:256
	v_add_lshl_u32 v184, v158, v172, 1
	global_load_dwordx4 v[242:245], v184, s[40:41]
	global_load_dwordx4 v[246:249], v184, s[40:41] offset:256
	s_waitcnt vmcnt(11)
	v_lshlrev_b32_e32 v180, 16, v192
	v_and_b32_e32 v181, 0xffff0000, v192
	v_lshlrev_b32_e32 v182, 16, v193
	v_and_b32_e32 v183, 0xffff0000, v193
	v_lshlrev_b32_e32 v192, 16, v194
	v_and_b32_e32 v193, 0xffff0000, v194
	v_lshlrev_b32_e32 v194, 16, v195
	v_and_b32_e32 v195, 0xffff0000, v195
	v_pk_fma_f32 v[140:141], v[140:141], v[128:129], v[180:181]
	v_pk_fma_f32 v[142:143], v[142:143], v[130:131], v[182:183]
	v_pk_fma_f32 v[136:137], v[136:137], v[124:125], v[192:193]
	v_pk_fma_f32 v[138:139], v[138:139], v[126:127], v[194:195]
	v_cvt_pk_bf16_f32 v140, v140, v141
	v_cvt_pk_bf16_f32 v141, v142, v143
	v_cvt_pk_bf16_f32 v142, v136, v137
	v_cvt_pk_bf16_f32 v143, v138, v139
	v_add_lshl_u32 v186, v148, v172, 1
	global_store_dwordx4 v186, v[140:143], s[38:39]
	s_waitcnt vmcnt(11)
	v_lshlrev_b32_e32 v180, 16, v196
	v_and_b32_e32 v181, 0xffff0000, v196
	v_lshlrev_b32_e32 v182, 16, v197
	v_and_b32_e32 v183, 0xffff0000, v197
	v_lshlrev_b32_e32 v196, 16, v198
	v_and_b32_e32 v197, 0xffff0000, v198
	v_lshlrev_b32_e32 v198, 16, v199
	v_and_b32_e32 v199, 0xffff0000, v199
	v_pk_fma_f32 v[132:133], v[132:133], v[108:109], v[180:181]
	v_pk_fma_f32 v[134:135], v[134:135], v[110:111], v[182:183]
	v_pk_fma_f32 v[120:121], v[120:121], v[104:105], v[196:197]
	v_pk_fma_f32 v[122:123], v[122:123], v[106:107], v[198:199]
	v_cvt_pk_bf16_f32 v132, v132, v133
	v_cvt_pk_bf16_f32 v133, v134, v135
	v_cvt_pk_bf16_f32 v134, v120, v121
	v_cvt_pk_bf16_f32 v135, v122, v123
	global_store_dwordx4 v186, v[132:135], s[38:39] offset:256
	s_waitcnt vmcnt(11)
	v_lshlrev_b32_e32 v180, 16, v200
	v_and_b32_e32 v181, 0xffff0000, v200
	v_lshlrev_b32_e32 v182, 16, v201
	v_and_b32_e32 v183, 0xffff0000, v201
	v_lshlrev_b32_e32 v200, 16, v202
	v_and_b32_e32 v201, 0xffff0000, v202
	v_lshlrev_b32_e32 v202, 16, v203
	v_and_b32_e32 v203, 0xffff0000, v203
	v_pk_fma_f32 v[116:117], v[116:117], v[128:129], v[180:181]
	v_pk_fma_f32 v[118:119], v[118:119], v[130:131], v[182:183]
	v_pk_fma_f32 v[112:113], v[112:113], v[124:125], v[200:201]
	v_pk_fma_f32 v[114:115], v[114:115], v[126:127], v[202:203]
	v_cvt_pk_bf16_f32 v116, v116, v117
	v_cvt_pk_bf16_f32 v117, v118, v119
	v_cvt_pk_bf16_f32 v118, v112, v113
	v_cvt_pk_bf16_f32 v119, v114, v115
	v_add_lshl_u32 v186, v150, v172, 1
	global_store_dwordx4 v186, v[116:119], s[38:39]
	s_waitcnt vmcnt(11)
	v_lshlrev_b32_e32 v180, 16, v208
	v_and_b32_e32 v181, 0xffff0000, v208
	v_lshlrev_b32_e32 v182, 16, v209
	v_and_b32_e32 v183, 0xffff0000, v209
	v_lshlrev_b32_e32 v208, 16, v210
	v_and_b32_e32 v209, 0xffff0000, v210
	v_lshlrev_b32_e32 v210, 16, v211
	v_and_b32_e32 v211, 0xffff0000, v211
	v_pk_fma_f32 v[100:101], v[100:101], v[108:109], v[180:181]
	v_pk_fma_f32 v[102:103], v[102:103], v[110:111], v[182:183]
	v_pk_fma_f32 v[96:97], v[96:97], v[104:105], v[208:209]
	v_pk_fma_f32 v[98:99], v[98:99], v[106:107], v[210:211]
	v_cvt_pk_bf16_f32 v100, v100, v101
	v_cvt_pk_bf16_f32 v101, v102, v103
	v_cvt_pk_bf16_f32 v102, v96, v97
	v_cvt_pk_bf16_f32 v103, v98, v99
	global_store_dwordx4 v186, v[100:103], s[38:39] offset:256
	v_add_lshl_u32 v185, v160, v172, 1
	global_load_dwordx4 v[192:195], v185, s[40:41]
	global_load_dwordx4 v[196:199], v185, s[40:41] offset:256
	v_add_lshl_u32 v184, v162, v172, 1
	global_load_dwordx4 v[200:203], v184, s[40:41]
	global_load_dwordx4 v[208:211], v184, s[40:41] offset:256
	s_waitcnt vmcnt(15)
	v_lshlrev_b32_e32 v180, 16, v212
	v_and_b32_e32 v181, 0xffff0000, v212
	v_lshlrev_b32_e32 v182, 16, v213
	v_and_b32_e32 v183, 0xffff0000, v213
	v_lshlrev_b32_e32 v212, 16, v214
	v_and_b32_e32 v213, 0xffff0000, v214
	v_lshlrev_b32_e32 v214, 16, v215
	v_and_b32_e32 v215, 0xffff0000, v215
	v_pk_fma_f32 v[92:93], v[92:93], v[128:129], v[180:181]
	v_pk_fma_f32 v[94:95], v[94:95], v[130:131], v[182:183]
	v_pk_fma_f32 v[88:89], v[88:89], v[124:125], v[212:213]
	v_pk_fma_f32 v[90:91], v[90:91], v[126:127], v[214:215]
	v_cvt_pk_bf16_f32 v92, v92, v93
	v_cvt_pk_bf16_f32 v93, v94, v95
	v_cvt_pk_bf16_f32 v94, v88, v89
	v_cvt_pk_bf16_f32 v95, v90, v91
	v_add_lshl_u32 v186, v152, v172, 1
	global_store_dwordx4 v186, v[92:95], s[38:39]
	s_waitcnt vmcnt(15)
; __device__ __forceinline__ unsigned cvt_pk_bf16(float lo, float hi) { unsigned r; asm("v_cvt_pk_bf16_f32 %0, %1, %2" : "=v"(r) : "v"(lo), "v"(hi)); return r; }
;     __device__ __forceinline__ void operator()(const Acc& acc, const Unit& u, int wr, int wc, int fr, int fq) const {
;     ...
;             for (int m = 0; m < 4; ++m) { const size_t off = (size_t)(r0 + ai * 128 + m * 16) * D + col0;
; #pragma unroll
;                 for (int bj = 0; bj < 2; ++bj) { const size_t o2 = off + bj * 128; f32x4 s0, s1;
;                     if (SRC32) { s0 = *(const f32x4*)(sp32 + o2); s1 = *(const f32x4*)(sp32 + o2 + 4); }
;                     else { const u32x4 q = *(const u32x4*)(sp16 + o2); s0 = (f32x4){bf2f(q.x & 0xffffu), bf2f(q.x >> 16), bf2f(q.y & 0xffffu), bf2f(q.y >> 16)}; s1 = (f32x4){bf2f(q.z & 0xffffu), bf2f(q.z >> 16), bf2f(q.w & 0xffffu), bf2f(q.w >> 16)}; }
;                     const f32x4 v0 = s0 + gv[bj][0] * acc[ai][bj][m][0], v1 = s1 + gv[bj][1] * acc[ai][bj][m][1];
;                     if (DST32) { *(f32x4*)(dp32 + o2) = v0; *(f32x4*)(dp32 + o2 + 4) = v1; }
;                     else { u32x4 w; w.x = cvt_pk_bf16(v0.x, v0.y); w.y = cvt_pk_bf16(v0.z, v0.w); w.z = cvt_pk_bf16(v1.x, v1.y); w.w = cvt_pk_bf16(v1.z, v1.w); *(u32x4*)(dp16 + o2) = w; } } }
	v_lshlrev_b32_e32 v180, 16, v216
	v_and_b32_e32 v181, 0xffff0000, v216
	v_lshlrev_b32_e32 v182, 16, v217
	v_and_b32_e32 v183, 0xffff0000, v217
	v_lshlrev_b32_e32 v216, 16, v218
	v_and_b32_e32 v217, 0xffff0000, v218
	v_lshlrev_b32_e32 v218, 16, v219
	v_and_b32_e32 v219, 0xffff0000, v219
	v_pk_fma_f32 v[84:85], v[84:85], v[108:109], v[180:181]
	v_pk_fma_f32 v[86:87], v[86:87], v[110:111], v[182:183]
	v_pk_fma_f32 v[80:81], v[80:81], v[104:105], v[216:217]
	v_pk_fma_f32 v[82:83], v[82:83], v[106:107], v[218:219]
	v_cvt_pk_bf16_f32 v84, v84, v85
	v_cvt_pk_bf16_f32 v85, v86, v87
	v_cvt_pk_bf16_f32 v86, v80, v81
	v_cvt_pk_bf16_f32 v87, v82, v83
	global_store_dwordx4 v186, v[84:87], s[38:39] offset:256
	s_waitcnt vmcnt(15)
	v_lshlrev_b32_e32 v180, 16, v220
	v_and_b32_e32 v181, 0xffff0000, v220
	v_lshlrev_b32_e32 v182, 16, v221
	v_and_b32_e32 v183, 0xffff0000, v221
	v_lshlrev_b32_e32 v220, 16, v222
	v_and_b32_e32 v221, 0xffff0000, v222
	v_lshlrev_b32_e32 v222, 16, v223
	v_and_b32_e32 v223, 0xffff0000, v223
	v_pk_fma_f32 v[76:77], v[76:77], v[128:129], v[180:181]
	v_pk_fma_f32 v[78:79], v[78:79], v[130:131], v[182:183]
	v_pk_fma_f32 v[72:73], v[72:73], v[124:125], v[220:221]
	v_pk_fma_f32 v[74:75], v[74:75], v[126:127], v[222:223]
	v_cvt_pk_bf16_f32 v76, v76, v77
	v_cvt_pk_bf16_f32 v77, v78, v79
	v_cvt_pk_bf16_f32 v78, v72, v73
	v_cvt_pk_bf16_f32 v79, v74, v75
	v_add_lshl_u32 v186, v154, v172, 1
	global_store_dwordx4 v186, v[76:79], s[38:39]
	s_waitcnt vmcnt(15)
	v_lshlrev_b32_e32 v180, 16, v224
	v_and_b32_e32 v181, 0xffff0000, v224
	v_lshlrev_b32_e32 v182, 16, v225
	v_and_b32_e32 v183, 0xffff0000, v225
	v_lshlrev_b32_e32 v224, 16, v226
	v_and_b32_e32 v225, 0xffff0000, v226
	v_lshlrev_b32_e32 v226, 16, v227
	v_and_b32_e32 v227, 0xffff0000, v227
	v_pk_fma_f32 v[68:69], v[68:69], v[108:109], v[180:181]
	v_pk_fma_f32 v[70:71], v[70:71], v[110:111], v[182:183]
	v_pk_fma_f32 v[64:65], v[64:65], v[104:105], v[224:225]
	v_pk_fma_f32 v[66:67], v[66:67], v[106:107], v[226:227]
	v_cvt_pk_bf16_f32 v68, v68, v69
	v_cvt_pk_bf16_f32 v69, v70, v71
	v_cvt_pk_bf16_f32 v70, v64, v65
	v_cvt_pk_bf16_f32 v71, v66, v67
	global_store_dwordx4 v186, v[68:71], s[38:39] offset:256
	s_waitcnt vmcnt(15)
	v_lshlrev_b32_e32 v180, 16, v228
	v_and_b32_e32 v181, 0xffff0000, v228
	v_lshlrev_b32_e32 v182, 16, v229
	v_and_b32_e32 v183, 0xffff0000, v229
	v_lshlrev_b32_e32 v228, 16, v230
	v_and_b32_e32 v229, 0xffff0000, v230
	v_lshlrev_b32_e32 v230, 16, v231
	v_and_b32_e32 v231, 0xffff0000, v231
	v_pk_fma_f32 v[60:61], v[60:61], v[128:129], v[180:181]
	v_pk_fma_f32 v[62:63], v[62:63], v[130:131], v[182:183]
	v_pk_fma_f32 v[56:57], v[56:57], v[124:125], v[228:229]
	v_pk_fma_f32 v[58:59], v[58:59], v[126:127], v[230:231]
	v_cvt_pk_bf16_f32 v60, v60, v61
	v_cvt_pk_bf16_f32 v61, v62, v63
	v_cvt_pk_bf16_f32 v62, v56, v57
	v_cvt_pk_bf16_f32 v63, v58, v59
	v_add_lshl_u32 v186, v156, v172, 1
	global_store_dwordx4 v186, v[60:63], s[38:39]
	s_waitcnt vmcnt(15)
	v_lshlrev_b32_e32 v180, 16, v238
	v_and_b32_e32 v181, 0xffff0000, v238
	v_lshlrev_b32_e32 v182, 16, v239
	v_and_b32_e32 v183, 0xffff0000, v239
	v_lshlrev_b32_e32 v238, 16, v240
	v_and_b32_e32 v239, 0xffff0000, v240
	v_lshlrev_b32_e32 v240, 16, v241
	v_and_b32_e32 v241, 0xffff0000, v241
	v_pk_fma_f32 v[52:53], v[52:53], v[108:109], v[180:181]
	v_pk_fma_f32 v[54:55], v[54:55], v[110:111], v[182:183]
	v_pk_fma_f32 v[48:49], v[48:49], v[104:105], v[238:239]
	v_pk_fma_f32 v[50:51], v[50:51], v[106:107], v[240:241]
	v_cvt_pk_bf16_f32 v52, v52, v53
	v_cvt_pk_bf16_f32 v53, v54, v55
	v_cvt_pk_bf16_f32 v54, v48, v49
	v_cvt_pk_bf16_f32 v55, v50, v51
	global_store_dwordx4 v186, v[52:55], s[38:39] offset:256
	s_waitcnt vmcnt(15)
	v_lshlrev_b32_e32 v180, 16, v242
	v_and_b32_e32 v181, 0xffff0000, v242
	v_lshlrev_b32_e32 v182, 16, v243
	v_and_b32_e32 v183, 0xffff0000, v243
	v_lshlrev_b32_e32 v242, 16, v244
	v_and_b32_e32 v243, 0xffff0000, v244
	v_lshlrev_b32_e32 v244, 16, v245
	v_and_b32_e32 v245, 0xffff0000, v245
	v_pk_fma_f32 v[44:45], v[44:45], v[128:129], v[180:181]
	v_pk_fma_f32 v[46:47], v[46:47], v[130:131], v[182:183]
	v_pk_fma_f32 v[40:41], v[40:41], v[124:125], v[242:243]
	v_pk_fma_f32 v[42:43], v[42:43], v[126:127], v[244:245]
	v_cvt_pk_bf16_f32 v44, v44, v45
	v_cvt_pk_bf16_f32 v45, v46, v47
	v_cvt_pk_bf16_f32 v46, v40, v41
	v_cvt_pk_bf16_f32 v47, v42, v43
	v_add_lshl_u32 v186, v158, v172, 1
	global_store_dwordx4 v186, v[44:47], s[38:39]
	s_waitcnt vmcnt(15)
; __device__ __forceinline__ unsigned cvt_pk_bf16(float lo, float hi) { unsigned r; asm("v_cvt_pk_bf16_f32 %0, %1, %2" : "=v"(r) : "v"(lo), "v"(hi)); return r; }
; #define PG8_BAR __builtin_amdgcn_s_barrier()
; template <class Epi, class Sched, bool SWAPD = false>
; __device__ __forceinline__ void gemm_phase(LAS unsigned char* lds, const Gemm g, const Sched& S, const Epi& E) {
;     ...
;         if (!has_next) break;
; #pragma unroll
;         for (int a = 0; a < 2; ++a)
; #pragma unroll
;             for (int b = 0; b < 2; ++b)
; #pragma unroll
;                 for (int m = 0; m < 4; ++m)
; #pragma unroll
;                     for (int n = 0; n < 2; ++n) acc[a][b][m][n] = (f32x4){0.f, 0.f, 0.f, 0.f};
;         cur = nxt; cA = nA; cB = nB; ++ui;
;         if (wr == 1) PG8_BAR;
;     __device__ __forceinline__ void operator()(const Acc& acc, const Unit& u, int wr, int wc, int fr, int fq) const {
;     ...
;             for (int m = 0; m < 4; ++m) { const size_t off = (size_t)(r0 + ai * 128 + m * 16) * D + col0;
; #pragma unroll
;                 for (int bj = 0; bj < 2; ++bj) { const size_t o2 = off + bj * 128; f32x4 s0, s1;
;                     if (SRC32) { s0 = *(const f32x4*)(sp32 + o2); s1 = *(const f32x4*)(sp32 + o2 + 4); }
;                     else { const u32x4 q = *(const u32x4*)(sp16 + o2); s0 = (f32x4){bf2f(q.x & 0xffffu), bf2f(q.x >> 16), bf2f(q.y & 0xffffu), bf2f(q.y >> 16)}; s1 = (f32x4){bf2f(q.z & 0xffffu), bf2f(q.z >> 16), bf2f(q.w & 0xffffu), bf2f(q.w >> 16)}; }
;                     const f32x4 v0 = s0 + gv[bj][0] * acc[ai][bj][m][0], v1 = s1 + gv[bj][1] * acc[ai][bj][m][1];
;                     if (DST32) { *(f32x4*)(dp32 + o2) = v0; *(f32x4*)(dp32 + o2 + 4) = v1; }
;                     else { u32x4 w; w.x = cvt_pk_bf16(v0.x, v0.y); w.y = cvt_pk_bf16(v0.z, v0.w); w.z = cvt_pk_bf16(v1.x, v1.y); w.w = cvt_pk_bf16(v1.z, v1.w); *(u32x4*)(dp16 + o2) = w; } } }
	v_lshlrev_b32_e32 v180, 16, v246
	v_and_b32_e32 v181, 0xffff0000, v246
	v_lshlrev_b32_e32 v182, 16, v247
	v_and_b32_e32 v183, 0xffff0000, v247
	v_lshlrev_b32_e32 v246, 16, v248
	v_and_b32_e32 v247, 0xffff0000, v248
	v_lshlrev_b32_e32 v248, 16, v249
	v_and_b32_e32 v249, 0xffff0000, v249
	v_pk_fma_f32 v[36:37], v[36:37], v[108:109], v[180:181]
	v_pk_fma_f32 v[38:39], v[38:39], v[110:111], v[182:183]
	v_pk_fma_f32 v[32:33], v[32:33], v[104:105], v[246:247]
	v_pk_fma_f32 v[34:35], v[34:35], v[106:107], v[248:249]
	v_cvt_pk_bf16_f32 v36, v36, v37
	v_cvt_pk_bf16_f32 v37, v38, v39
	v_cvt_pk_bf16_f32 v38, v32, v33
	v_cvt_pk_bf16_f32 v39, v34, v35
	global_store_dwordx4 v186, v[36:39], s[38:39] offset:256
	s_waitcnt vmcnt(11)
	v_lshlrev_b32_e32 v180, 16, v192
	v_and_b32_e32 v181, 0xffff0000, v192
	v_lshlrev_b32_e32 v182, 16, v193
	v_and_b32_e32 v183, 0xffff0000, v193
	v_lshlrev_b32_e32 v192, 16, v194
	v_and_b32_e32 v193, 0xffff0000, v194
	v_lshlrev_b32_e32 v194, 16, v195
	v_and_b32_e32 v195, 0xffff0000, v195
	v_pk_fma_f32 v[28:29], v[28:29], v[128:129], v[180:181]
	v_pk_fma_f32 v[30:31], v[30:31], v[130:131], v[182:183]
	v_pk_fma_f32 v[24:25], v[24:25], v[124:125], v[192:193]
	v_pk_fma_f32 v[26:27], v[26:27], v[126:127], v[194:195]
	v_cvt_pk_bf16_f32 v28, v28, v29
	v_cvt_pk_bf16_f32 v29, v30, v31
	v_cvt_pk_bf16_f32 v30, v24, v25
	v_cvt_pk_bf16_f32 v31, v26, v27
	v_add_lshl_u32 v186, v160, v172, 1
	global_store_dwordx4 v186, v[28:31], s[38:39]
	s_waitcnt vmcnt(11)
	v_lshlrev_b32_e32 v180, 16, v196
	v_and_b32_e32 v181, 0xffff0000, v196
	v_lshlrev_b32_e32 v182, 16, v197
	v_and_b32_e32 v183, 0xffff0000, v197
	v_lshlrev_b32_e32 v196, 16, v198
	v_and_b32_e32 v197, 0xffff0000, v198
	v_lshlrev_b32_e32 v198, 16, v199
	v_and_b32_e32 v199, 0xffff0000, v199
	v_pk_fma_f32 v[20:21], v[20:21], v[108:109], v[180:181]
	v_pk_fma_f32 v[22:23], v[22:23], v[110:111], v[182:183]
	v_pk_fma_f32 v[16:17], v[16:17], v[104:105], v[196:197]
	v_pk_fma_f32 v[18:19], v[18:19], v[106:107], v[198:199]
	v_cvt_pk_bf16_f32 v20, v20, v21
	v_cvt_pk_bf16_f32 v21, v22, v23
	v_cvt_pk_bf16_f32 v22, v16, v17
	v_cvt_pk_bf16_f32 v23, v18, v19
	global_store_dwordx4 v186, v[20:23], s[38:39] offset:256
	s_waitcnt vmcnt(11)
	v_lshlrev_b32_e32 v180, 16, v200
	v_and_b32_e32 v181, 0xffff0000, v200
	v_lshlrev_b32_e32 v182, 16, v201
	v_and_b32_e32 v183, 0xffff0000, v201
	v_lshlrev_b32_e32 v200, 16, v202
	v_and_b32_e32 v201, 0xffff0000, v202
	v_lshlrev_b32_e32 v202, 16, v203
	v_and_b32_e32 v203, 0xffff0000, v203
	v_pk_fma_f32 v[12:13], v[12:13], v[128:129], v[180:181]
	v_pk_fma_f32 v[14:15], v[14:15], v[130:131], v[182:183]
	v_pk_fma_f32 v[8:9], v[8:9], v[124:125], v[200:201]
	v_pk_fma_f32 v[10:11], v[10:11], v[126:127], v[202:203]
	v_cvt_pk_bf16_f32 v12, v12, v13
	v_cvt_pk_bf16_f32 v13, v14, v15
	v_cvt_pk_bf16_f32 v14, v8, v9
	v_cvt_pk_bf16_f32 v15, v10, v11
	v_add_lshl_u32 v186, v162, v172, 1
	global_store_dwordx4 v186, v[12:15], s[38:39]
	s_waitcnt vmcnt(11)
	v_lshlrev_b32_e32 v180, 16, v208
	v_and_b32_e32 v181, 0xffff0000, v208
	v_lshlrev_b32_e32 v182, 16, v209
	v_and_b32_e32 v183, 0xffff0000, v209
	v_lshlrev_b32_e32 v208, 16, v210
	v_and_b32_e32 v209, 0xffff0000, v210
	v_lshlrev_b32_e32 v210, 16, v211
	v_and_b32_e32 v211, 0xffff0000, v211
	v_pk_fma_f32 v[4:5], v[4:5], v[108:109], v[180:181]
	v_pk_fma_f32 v[6:7], v[6:7], v[110:111], v[182:183]
	v_pk_fma_f32 v[0:1], v[0:1], v[104:105], v[208:209]
	v_pk_fma_f32 v[2:3], v[2:3], v[106:107], v[210:211]
	v_cvt_pk_bf16_f32 v4, v4, v5
	v_cvt_pk_bf16_f32 v5, v6, v7
	v_cvt_pk_bf16_f32 v6, v0, v1
	v_cvt_pk_bf16_f32 v7, v2, v3
	global_store_dwordx4 v186, v[4:7], s[38:39] offset:256
	s_andn2_b64 vcc, exec, s[6:7]
	s_mov_b64 s[6:7], -1
	s_cbranch_vccnz .LBB0_1729
	s_andn2_b64 vcc, exec, s[0:1]
	s_cbranch_vccnz .LBB0_1728
	s_barrier
	s_branch .LBB0_1728

; __device__ __forceinline__ unsigned cvt_pk_bf16(float lo, float hi) { unsigned r; asm("v_cvt_pk_bf16_f32 %0, %1, %2" : "=v"(r) : "v"(lo), "v"(hi)); return r; }
;     __device__ __forceinline__ void operator()(const Acc& acc, const Unit& u, int wr, int wc, int fr, int fq) const {
;         const bool isx = u.pm < 128; const int mb = isx ? (u.pm >> 4) : 8;
;         const size_t tile0 = (size_t)(isx ? u.pm : u.pm - 128) * 256 * D;
;         const float* sp32 = (const float*)(isx ? srcx : srcc) + tile0; const bf16_t* sp16 = (const bf16_t*)(isx ? srcx : srcc) + tile0;
;         float* dp32 = (float*)(isx ? dstx : dstc) + tile0; bf16_t* dp16 = (bf16_t*)(isx ? dstx : dstc) + tile0;
;         const int r0 = wr * 64 + fr, col0 = u.pn * 256 + wc * 32 + 8 * fq; const float* gp = gate + (size_t)mb * 9216 + col0;
;         f32x4 gv[2][2];
; #pragma unroll
;         for (int bj = 0; bj < 2; ++bj)
; #pragma unroll
;             for (int n = 0; n < 2; ++n) gv[bj][n] = *(const f32x4*)(gp + bj * 128 + n * 4) * f;
; #pragma unroll
;         for (int ai = 0; ai < 2; ++ai)
; #pragma unroll
;             for (int m = 0; m < 4; ++m) { const size_t off = (size_t)(r0 + ai * 128 + m * 16) * D + col0;
; #pragma unroll
;                 for (int bj = 0; bj < 2; ++bj) { const size_t o2 = off + bj * 128; f32x4 s0, s1;
;                     if (SRC32) { s0 = *(const f32x4*)(sp32 + o2); s1 = *(const f32x4*)(sp32 + o2 + 4); }
;                     else { const u32x4 q = *(const u32x4*)(sp16 + o2); s0 = (f32x4){bf2f(q.x & 0xffffu), bf2f(q.x >> 16), bf2f(q.y & 0xffffu), bf2f(q.y >> 16)}; s1 = (f32x4){bf2f(q.z & 0xffffu), bf2f(q.z >> 16), bf2f(q.w & 0xffffu), bf2f(q.w >> 16)}; }
;                     const f32x4 v0 = s0 + gv[bj][0] * acc[ai][bj][m][0], v1 = s1 + gv[bj][1] * acc[ai][bj][m][1];
;                     if (DST32) { *(f32x4*)(dp32 + o2) = v0; *(f32x4*)(dp32 + o2 + 4) = v1; }
;                     else { u32x4 w; w.x = cvt_pk_bf16(v0.x, v0.y); w.y = cvt_pk_bf16(v0.z, v0.w); w.z = cvt_pk_bf16(v1.x, v1.y); w.w = cvt_pk_bf16(v1.z, v1.w); *(u32x4*)(dp16 + o2) = w; } } }
.LBB0_1945:
	s_add_i32 s24, s45, 0xffffff80
	s_and_b64 s[22:23], s[22:23], exec
	s_cselect_b32 s24, s45, s24
	s_ashr_i32 s25, s24, 31
	s_lshl_b64 s[20:21], s[20:21], 2
	v_lshl_or_b32 v242, s46, 8, v167
	s_add_u32 s20, s37, s20
	s_addc_u32 s21, s38, s21
	v_lshlrev_b32_e32 v240, 2, v242
	global_load_dwordx4 v[156:159], v240, s[20:21]
	global_load_dwordx4 v[160:163], v240, s[20:21] offset:16
	global_load_dwordx4 v[172:175], v240, s[20:21] offset:512
	global_load_dwordx4 v[176:179], v240, s[20:21] offset:528
	s_lshl_b64 s[20:21], s[24:25], 19
	s_add_u32 s22, s72, s20
	s_addc_u32 s23, s73, s21
	s_lshl_b64 s[20:21], s[24:25], 20
	s_add_u32 s20, s86, s20
	s_addc_u32 s21, s87, s21
	v_add_lshl_u32 v241, v132, v242, 1
	global_load_dwordx4 v[180:183], v241, s[22:23]
	global_load_dwordx4 v[184:187], v241, s[22:23] offset:256
	v_add_lshl_u32 v240, v134, v242, 1
	global_load_dwordx4 v[188:191], v240, s[22:23]
	global_load_dwordx4 v[192:195], v240, s[22:23] offset:256
	v_add_lshl_u32 v241, v136, v242, 1
	global_load_dwordx4 v[196:199], v241, s[22:23]
	global_load_dwordx4 v[200:203], v241, s[22:23] offset:256
	v_add_lshl_u32 v240, v138, v242, 1
	global_load_dwordx4 v[204:207], v240, s[22:23]
	global_load_dwordx4 v[208:211], v240, s[22:23] offset:256
	v_add_lshl_u32 v241, v140, v242, 1
	global_load_dwordx4 v[212:215], v241, s[22:23]
	global_load_dwordx4 v[216:219], v241, s[22:23] offset:256
	v_add_lshl_u32 v240, v142, v242, 1
	global_load_dwordx4 v[220:223], v240, s[22:23]
	global_load_dwordx4 v[224:227], v240, s[22:23] offset:256
	s_waitcnt vmcnt(11)
	v_pk_mul_f32 v[156:157], v[156:157], 0.5 op_sel_hi:[1,0]
	v_pk_mul_f32 v[158:159], v[158:159], 0.5 op_sel_hi:[1,0]
	v_pk_mul_f32 v[160:161], v[160:161], 0.5 op_sel_hi:[1,0]
	v_pk_mul_f32 v[162:163], v[162:163], 0.5 op_sel_hi:[1,0]
	v_pk_mul_f32 v[172:173], v[172:173], 0.5 op_sel_hi:[1,0]
	v_pk_mul_f32 v[174:175], v[174:175], 0.5 op_sel_hi:[1,0]
	v_pk_mul_f32 v[176:177], v[176:177], 0.5 op_sel_hi:[1,0]
	v_pk_mul_f32 v[178:179], v[178:179], 0.5 op_sel_hi:[1,0]
	v_lshlrev_b32_e32 v236, 16, v180
	v_and_b32_e32 v237, 0xffff0000, v180
	v_lshlrev_b32_e32 v238, 16, v181
	v_and_b32_e32 v239, 0xffff0000, v181
	v_lshlrev_b32_e32 v180, 16, v182
	v_and_b32_e32 v181, 0xffff0000, v182
	v_lshlrev_b32_e32 v182, 16, v183
	v_and_b32_e32 v183, 0xffff0000, v183
	v_pk_fma_f32 v[124:125], v[124:125], v[156:157], v[236:237]
	v_pk_fma_f32 v[126:127], v[126:127], v[158:159], v[238:239]
	v_pk_fma_f32 v[120:121], v[120:121], v[160:161], v[180:181]
	v_pk_fma_f32 v[122:123], v[122:123], v[162:163], v[182:183]
	v_add_lshl_u32 v243, v132, v242, 2
	global_store_dwordx4 v243, v[124:127], s[20:21]
	global_store_dwordx4 v243, v[120:123], s[20:21] offset:16
	s_waitcnt vmcnt(12)
	v_lshlrev_b32_e32 v236, 16, v184
	v_and_b32_e32 v237, 0xffff0000, v184
	v_lshlrev_b32_e32 v238, 16, v185
	v_and_b32_e32 v239, 0xffff0000, v185
	v_lshlrev_b32_e32 v184, 16, v186
	v_and_b32_e32 v185, 0xffff0000, v186
	v_lshlrev_b32_e32 v186, 16, v187
	v_and_b32_e32 v187, 0xffff0000, v187
	v_pk_fma_f32 v[116:117], v[116:117], v[172:173], v[236:237]
	v_pk_fma_f32 v[118:119], v[118:119], v[174:175], v[238:239]
	v_pk_fma_f32 v[112:113], v[112:113], v[176:177], v[184:185]
	v_pk_fma_f32 v[114:115], v[114:115], v[178:179], v[186:187]
	global_store_dwordx4 v243, v[116:119], s[20:21] offset:512
	global_store_dwordx4 v243, v[112:115], s[20:21] offset:528
	s_waitcnt vmcnt(13)
	v_lshlrev_b32_e32 v236, 16, v188
	v_and_b32_e32 v237, 0xffff0000, v188
	v_lshlrev_b32_e32 v238, 16, v189
	v_and_b32_e32 v239, 0xffff0000, v189
	v_lshlrev_b32_e32 v188, 16, v190
	v_and_b32_e32 v189, 0xffff0000, v190
	v_lshlrev_b32_e32 v190, 16, v191
	v_and_b32_e32 v191, 0xffff0000, v191
	v_pk_fma_f32 v[108:109], v[108:109], v[156:157], v[236:237]
	v_pk_fma_f32 v[110:111], v[110:111], v[158:159], v[238:239]
	v_pk_fma_f32 v[104:105], v[104:105], v[160:161], v[188:189]
	v_pk_fma_f32 v[106:107], v[106:107], v[162:163], v[190:191]
	v_add_lshl_u32 v243, v134, v242, 2
	global_store_dwordx4 v243, v[108:111], s[20:21]
	global_store_dwordx4 v243, v[104:107], s[20:21] offset:16
	s_waitcnt vmcnt(14)
	v_lshlrev_b32_e32 v236, 16, v192
	v_and_b32_e32 v237, 0xffff0000, v192
	v_lshlrev_b32_e32 v238, 16, v193
	v_and_b32_e32 v239, 0xffff0000, v193
	v_lshlrev_b32_e32 v192, 16, v194
	v_and_b32_e32 v193, 0xffff0000, v194
	v_lshlrev_b32_e32 v194, 16, v195
	v_and_b32_e32 v195, 0xffff0000, v195
	v_pk_fma_f32 v[100:101], v[100:101], v[172:173], v[236:237]
	v_pk_fma_f32 v[102:103], v[102:103], v[174:175], v[238:239]
	v_pk_fma_f32 v[96:97], v[96:97], v[176:177], v[192:193]
	v_pk_fma_f32 v[98:99], v[98:99], v[178:179], v[194:195]
	global_store_dwordx4 v243, v[100:103], s[20:21] offset:512
	global_store_dwordx4 v243, v[96:99], s[20:21] offset:528
	v_add_lshl_u32 v241, v144, v242, 1
	global_load_dwordx4 v[180:183], v241, s[22:23]
	global_load_dwordx4 v[184:187], v241, s[22:23] offset:256
	v_add_lshl_u32 v240, v146, v242, 1
	global_load_dwordx4 v[188:191], v240, s[22:23]
	global_load_dwordx4 v[192:195], v240, s[22:23] offset:256
	s_waitcnt vmcnt(19)
	v_lshlrev_b32_e32 v236, 16, v196
	v_and_b32_e32 v237, 0xffff0000, v196
	v_lshlrev_b32_e32 v238, 16, v197
	v_and_b32_e32 v239, 0xffff0000, v197
	v_lshlrev_b32_e32 v196, 16, v198
	v_and_b32_e32 v197, 0xffff0000, v198
	v_lshlrev_b32_e32 v198, 16, v199
	v_and_b32_e32 v199, 0xffff0000, v199
	v_pk_fma_f32 v[92:93], v[92:93], v[156:157], v[236:237]
	v_pk_fma_f32 v[94:95], v[94:95], v[158:159], v[238:239]
	v_pk_fma_f32 v[88:89], v[88:89], v[160:161], v[196:197]
	v_pk_fma_f32 v[90:91], v[90:91], v[162:163], v[198:199]
	v_add_lshl_u32 v243, v136, v242, 2
	global_store_dwordx4 v243, v[92:95], s[20:21]
	global_store_dwordx4 v243, v[88:91], s[20:21] offset:16
	s_waitcnt vmcnt(20)
; __device__ __forceinline__ unsigned cvt_pk_bf16(float lo, float hi) { unsigned r; asm("v_cvt_pk_bf16_f32 %0, %1, %2" : "=v"(r) : "v"(lo), "v"(hi)); return r; }
;     __device__ __forceinline__ void operator()(const Acc& acc, const Unit& u, int wr, int wc, int fr, int fq) const {
;     ...
;             for (int m = 0; m < 4; ++m) { const size_t off = (size_t)(r0 + ai * 128 + m * 16) * D + col0;
; #pragma unroll
;                 for (int bj = 0; bj < 2; ++bj) { const size_t o2 = off + bj * 128; f32x4 s0, s1;
;                     if (SRC32) { s0 = *(const f32x4*)(sp32 + o2); s1 = *(const f32x4*)(sp32 + o2 + 4); }
;                     else { const u32x4 q = *(const u32x4*)(sp16 + o2); s0 = (f32x4){bf2f(q.x & 0xffffu), bf2f(q.x >> 16), bf2f(q.y & 0xffffu), bf2f(q.y >> 16)}; s1 = (f32x4){bf2f(q.z & 0xffffu), bf2f(q.z >> 16), bf2f(q.w & 0xffffu), bf2f(q.w >> 16)}; }
;                     const f32x4 v0 = s0 + gv[bj][0] * acc[ai][bj][m][0], v1 = s1 + gv[bj][1] * acc[ai][bj][m][1];
;                     if (DST32) { *(f32x4*)(dp32 + o2) = v0; *(f32x4*)(dp32 + o2 + 4) = v1; }
;                     else { u32x4 w; w.x = cvt_pk_bf16(v0.x, v0.y); w.y = cvt_pk_bf16(v0.z, v0.w); w.z = cvt_pk_bf16(v1.x, v1.y); w.w = cvt_pk_bf16(v1.z, v1.w); *(u32x4*)(dp16 + o2) = w; } } }
	v_lshlrev_b32_e32 v236, 16, v200
	v_and_b32_e32 v237, 0xffff0000, v200
	v_lshlrev_b32_e32 v238, 16, v201
	v_and_b32_e32 v239, 0xffff0000, v201
	v_lshlrev_b32_e32 v200, 16, v202
	v_and_b32_e32 v201, 0xffff0000, v202
	v_lshlrev_b32_e32 v202, 16, v203
	v_and_b32_e32 v203, 0xffff0000, v203
	v_pk_fma_f32 v[84:85], v[84:85], v[172:173], v[236:237]
	v_pk_fma_f32 v[86:87], v[86:87], v[174:175], v[238:239]
	v_pk_fma_f32 v[80:81], v[80:81], v[176:177], v[200:201]
	v_pk_fma_f32 v[82:83], v[82:83], v[178:179], v[202:203]
	global_store_dwordx4 v243, v[84:87], s[20:21] offset:512
	global_store_dwordx4 v243, v[80:83], s[20:21] offset:528
	s_waitcnt vmcnt(21)
	v_lshlrev_b32_e32 v236, 16, v204
	v_and_b32_e32 v237, 0xffff0000, v204
	v_lshlrev_b32_e32 v238, 16, v205
	v_and_b32_e32 v239, 0xffff0000, v205
	v_lshlrev_b32_e32 v204, 16, v206
	v_and_b32_e32 v205, 0xffff0000, v206
	v_lshlrev_b32_e32 v206, 16, v207
	v_and_b32_e32 v207, 0xffff0000, v207
	v_pk_fma_f32 v[76:77], v[76:77], v[156:157], v[236:237]
	v_pk_fma_f32 v[78:79], v[78:79], v[158:159], v[238:239]
	v_pk_fma_f32 v[72:73], v[72:73], v[160:161], v[204:205]
	v_pk_fma_f32 v[74:75], v[74:75], v[162:163], v[206:207]
	v_add_lshl_u32 v243, v138, v242, 2
	global_store_dwordx4 v243, v[76:79], s[20:21]
	global_store_dwordx4 v243, v[72:75], s[20:21] offset:16
	s_waitcnt vmcnt(22)
	v_lshlrev_b32_e32 v236, 16, v208
	v_and_b32_e32 v237, 0xffff0000, v208
	v_lshlrev_b32_e32 v238, 16, v209
	v_and_b32_e32 v239, 0xffff0000, v209
	v_lshlrev_b32_e32 v208, 16, v210
	v_and_b32_e32 v209, 0xffff0000, v210
	v_lshlrev_b32_e32 v210, 16, v211
	v_and_b32_e32 v211, 0xffff0000, v211
	v_pk_fma_f32 v[68:69], v[68:69], v[172:173], v[236:237]
	v_pk_fma_f32 v[70:71], v[70:71], v[174:175], v[238:239]
	v_pk_fma_f32 v[64:65], v[64:65], v[176:177], v[208:209]
	v_pk_fma_f32 v[66:67], v[66:67], v[178:179], v[210:211]
	global_store_dwordx4 v243, v[68:71], s[20:21] offset:512
	global_store_dwordx4 v243, v[64:67], s[20:21] offset:528
	s_waitcnt vmcnt(23)
	v_lshlrev_b32_e32 v236, 16, v212
	v_and_b32_e32 v237, 0xffff0000, v212
	v_lshlrev_b32_e32 v238, 16, v213
	v_and_b32_e32 v239, 0xffff0000, v213
	v_lshlrev_b32_e32 v212, 16, v214
	v_and_b32_e32 v213, 0xffff0000, v214
	v_lshlrev_b32_e32 v214, 16, v215
	v_and_b32_e32 v215, 0xffff0000, v215
	v_pk_fma_f32 v[60:61], v[60:61], v[156:157], v[236:237]
	v_pk_fma_f32 v[62:63], v[62:63], v[158:159], v[238:239]
	v_pk_fma_f32 v[56:57], v[56:57], v[160:161], v[212:213]
	v_pk_fma_f32 v[58:59], v[58:59], v[162:163], v[214:215]
	v_add_lshl_u32 v243, v140, v242, 2
	global_store_dwordx4 v243, v[60:63], s[20:21]
	global_store_dwordx4 v243, v[56:59], s[20:21] offset:16
	s_waitcnt vmcnt(24)
	v_lshlrev_b32_e32 v236, 16, v216
	v_and_b32_e32 v237, 0xffff0000, v216
	v_lshlrev_b32_e32 v238, 16, v217
	v_and_b32_e32 v239, 0xffff0000, v217
	v_lshlrev_b32_e32 v216, 16, v218
	v_and_b32_e32 v217, 0xffff0000, v218
	v_lshlrev_b32_e32 v218, 16, v219
	v_and_b32_e32 v219, 0xffff0000, v219
	v_pk_fma_f32 v[52:53], v[52:53], v[172:173], v[236:237]
	v_pk_fma_f32 v[54:55], v[54:55], v[174:175], v[238:239]
	v_pk_fma_f32 v[48:49], v[48:49], v[176:177], v[216:217]
	v_pk_fma_f32 v[50:51], v[50:51], v[178:179], v[218:219]
	global_store_dwordx4 v243, v[52:55], s[20:21] offset:512
	global_store_dwordx4 v243, v[48:51], s[20:21] offset:528
	s_waitcnt vmcnt(25)
	v_lshlrev_b32_e32 v236, 16, v220
	v_and_b32_e32 v237, 0xffff0000, v220
	v_lshlrev_b32_e32 v238, 16, v221
	v_and_b32_e32 v239, 0xffff0000, v221
	v_lshlrev_b32_e32 v220, 16, v222
	v_and_b32_e32 v221, 0xffff0000, v222
	v_lshlrev_b32_e32 v222, 16, v223
	v_and_b32_e32 v223, 0xffff0000, v223
	v_pk_fma_f32 v[44:45], v[44:45], v[156:157], v[236:237]
	v_pk_fma_f32 v[46:47], v[46:47], v[158:159], v[238:239]
	v_pk_fma_f32 v[40:41], v[40:41], v[160:161], v[220:221]
	v_pk_fma_f32 v[42:43], v[42:43], v[162:163], v[222:223]
	v_add_lshl_u32 v243, v142, v242, 2
	global_store_dwordx4 v243, v[44:47], s[20:21]
	global_store_dwordx4 v243, v[40:43], s[20:21] offset:16
	s_waitcnt vmcnt(26)
; __device__ __forceinline__ unsigned cvt_pk_bf16(float lo, float hi) { unsigned r; asm("v_cvt_pk_bf16_f32 %0, %1, %2" : "=v"(r) : "v"(lo), "v"(hi)); return r; }
; #define PG8_BAR __builtin_amdgcn_s_barrier()
; template <class Epi, class Sched, bool SWAPD = false>
; __device__ __forceinline__ void gemm_phase(LAS unsigned char* lds, const Gemm g, const Sched& S, const Epi& E) {
;     ...
;         if (!has_next) break;
; #pragma unroll
;         for (int a = 0; a < 2; ++a)
; #pragma unroll
;             for (int b = 0; b < 2; ++b)
; #pragma unroll
;                 for (int m = 0; m < 4; ++m)
; #pragma unroll
;                     for (int n = 0; n < 2; ++n) acc[a][b][m][n] = (f32x4){0.f, 0.f, 0.f, 0.f};
;         cur = nxt; cA = nA; cB = nB; ++ui;
;         if (wr == 1) PG8_BAR;
;     __device__ __forceinline__ void operator()(const Acc& acc, const Unit& u, int wr, int wc, int fr, int fq) const {
;     ...
;             for (int m = 0; m < 4; ++m) { const size_t off = (size_t)(r0 + ai * 128 + m * 16) * D + col0;
; #pragma unroll
;                 for (int bj = 0; bj < 2; ++bj) { const size_t o2 = off + bj * 128; f32x4 s0, s1;
;                     if (SRC32) { s0 = *(const f32x4*)(sp32 + o2); s1 = *(const f32x4*)(sp32 + o2 + 4); }
;                     else { const u32x4 q = *(const u32x4*)(sp16 + o2); s0 = (f32x4){bf2f(q.x & 0xffffu), bf2f(q.x >> 16), bf2f(q.y & 0xffffu), bf2f(q.y >> 16)}; s1 = (f32x4){bf2f(q.z & 0xffffu), bf2f(q.z >> 16), bf2f(q.w & 0xffffu), bf2f(q.w >> 16)}; }
;                     const f32x4 v0 = s0 + gv[bj][0] * acc[ai][bj][m][0], v1 = s1 + gv[bj][1] * acc[ai][bj][m][1];
;                     if (DST32) { *(f32x4*)(dp32 + o2) = v0; *(f32x4*)(dp32 + o2 + 4) = v1; }
;                     else { u32x4 w; w.x = cvt_pk_bf16(v0.x, v0.y); w.y = cvt_pk_bf16(v0.z, v0.w); w.z = cvt_pk_bf16(v1.x, v1.y); w.w = cvt_pk_bf16(v1.z, v1.w); *(u32x4*)(dp16 + o2) = w; } } }
	v_lshlrev_b32_e32 v236, 16, v224
	v_and_b32_e32 v237, 0xffff0000, v224
	v_lshlrev_b32_e32 v238, 16, v225
	v_and_b32_e32 v239, 0xffff0000, v225
	v_lshlrev_b32_e32 v224, 16, v226
	v_and_b32_e32 v225, 0xffff0000, v226
	v_lshlrev_b32_e32 v226, 16, v227
	v_and_b32_e32 v227, 0xffff0000, v227
	v_pk_fma_f32 v[36:37], v[36:37], v[172:173], v[236:237]
	v_pk_fma_f32 v[38:39], v[38:39], v[174:175], v[238:239]
	v_pk_fma_f32 v[32:33], v[32:33], v[176:177], v[224:225]
	v_pk_fma_f32 v[34:35], v[34:35], v[178:179], v[226:227]
	global_store_dwordx4 v243, v[36:39], s[20:21] offset:512
	global_store_dwordx4 v243, v[32:35], s[20:21] offset:528
	s_waitcnt vmcnt(19)
	v_lshlrev_b32_e32 v236, 16, v180
	v_and_b32_e32 v237, 0xffff0000, v180
	v_lshlrev_b32_e32 v238, 16, v181
	v_and_b32_e32 v239, 0xffff0000, v181
	v_lshlrev_b32_e32 v180, 16, v182
	v_and_b32_e32 v181, 0xffff0000, v182
	v_lshlrev_b32_e32 v182, 16, v183
	v_and_b32_e32 v183, 0xffff0000, v183
	v_pk_fma_f32 v[28:29], v[28:29], v[156:157], v[236:237]
	v_pk_fma_f32 v[30:31], v[30:31], v[158:159], v[238:239]
	v_pk_fma_f32 v[24:25], v[24:25], v[160:161], v[180:181]
	v_pk_fma_f32 v[26:27], v[26:27], v[162:163], v[182:183]
	v_add_lshl_u32 v243, v144, v242, 2
	global_store_dwordx4 v243, v[28:31], s[20:21]
	global_store_dwordx4 v243, v[24:27], s[20:21] offset:16
	s_waitcnt vmcnt(20)
	v_lshlrev_b32_e32 v236, 16, v184
	v_and_b32_e32 v237, 0xffff0000, v184
	v_lshlrev_b32_e32 v238, 16, v185
	v_and_b32_e32 v239, 0xffff0000, v185
	v_lshlrev_b32_e32 v184, 16, v186
	v_and_b32_e32 v185, 0xffff0000, v186
	v_lshlrev_b32_e32 v186, 16, v187
	v_and_b32_e32 v187, 0xffff0000, v187
	v_pk_fma_f32 v[20:21], v[20:21], v[172:173], v[236:237]
	v_pk_fma_f32 v[22:23], v[22:23], v[174:175], v[238:239]
	v_pk_fma_f32 v[16:17], v[16:17], v[176:177], v[184:185]
	v_pk_fma_f32 v[18:19], v[18:19], v[178:179], v[186:187]
	global_store_dwordx4 v243, v[20:23], s[20:21] offset:512
	global_store_dwordx4 v243, v[16:19], s[20:21] offset:528
	s_waitcnt vmcnt(21)
	v_lshlrev_b32_e32 v236, 16, v188
	v_and_b32_e32 v237, 0xffff0000, v188
	v_lshlrev_b32_e32 v238, 16, v189
	v_and_b32_e32 v239, 0xffff0000, v189
	v_lshlrev_b32_e32 v188, 16, v190
	v_and_b32_e32 v189, 0xffff0000, v190
	v_lshlrev_b32_e32 v190, 16, v191
	v_and_b32_e32 v191, 0xffff0000, v191
	v_pk_fma_f32 v[12:13], v[12:13], v[156:157], v[236:237]
	v_pk_fma_f32 v[14:15], v[14:15], v[158:159], v[238:239]
	v_pk_fma_f32 v[8:9], v[8:9], v[160:161], v[188:189]
	v_pk_fma_f32 v[10:11], v[10:11], v[162:163], v[190:191]
	v_add_lshl_u32 v243, v146, v242, 2
	global_store_dwordx4 v243, v[12:15], s[20:21]
	global_store_dwordx4 v243, v[8:11], s[20:21] offset:16
	s_waitcnt vmcnt(22)
	v_lshlrev_b32_e32 v236, 16, v192
	v_and_b32_e32 v237, 0xffff0000, v192
	v_lshlrev_b32_e32 v238, 16, v193
	v_and_b32_e32 v239, 0xffff0000, v193
	v_lshlrev_b32_e32 v192, 16, v194
	v_and_b32_e32 v193, 0xffff0000, v194
	v_lshlrev_b32_e32 v194, 16, v195
	v_and_b32_e32 v195, 0xffff0000, v195
	v_pk_fma_f32 v[4:5], v[4:5], v[172:173], v[236:237]
	v_pk_fma_f32 v[6:7], v[6:7], v[174:175], v[238:239]
	v_pk_fma_f32 v[0:1], v[0:1], v[176:177], v[192:193]
	v_pk_fma_f32 v[2:3], v[2:3], v[178:179], v[194:195]
	global_store_dwordx4 v243, v[4:7], s[20:21] offset:512
	global_store_dwordx4 v243, v[0:3], s[20:21] offset:528
	s_andn2_b64 vcc, exec, s[0:1]
	s_mov_b64 s[0:1], -1
	s_cbranch_vccnz .LBB0_1932
	s_andn2_b64 vcc, exec, s[4:5]
	s_cbranch_vccnz .LBB0_1931
	s_barrier
	s_branch .LBB0_1931
